# GEMM loops: m0 write moved ahead of the LDS-DMA address VALU so the s_nop wait state is covered by a useful instruction (48 sites)
# baseline (speedup 1.0000x reference)
; #define PG8_STAGE(bufoff, gbase, voff) do { _Pragma("unroll") for (int _i = 0; _i < 2; ++_i) \
;         __builtin_amdgcn_global_load_lds((const unsigned*)((const char*)(gbase) + (voff)[_i]), (PG8_LAS unsigned*)(lds + (bufoff) + ldsw + _i * 8192), 16, 0, 0); } while (0)
; #define PG8_LDA(dst, b, h) do { _Pragma("unroll") for (int m = 0; m < 4; ++m) _Pragma("unroll") for (int k = 0; k < 2; ++k) dst[m][k] = *(const PG8_LAS bf16x8*)(lds + PG8_SA(b, h) + aoff + m * 2048 + k * 1024); } while (0)
; #define PG8_LDB(dst, b, h) do { _Pragma("unroll") for (int n = 0; n < 2; ++n) _Pragma("unroll") for (int k = 0; k < 2; ++k) dst[n][k] = *(const PG8_LAS bf16x8*)(lds + PG8_SB(b, h) + boff + n * 2048 + k * 1024); } while (0)
; #define PG8_MMA(ai, bj, At, Bt) do { __builtin_amdgcn_s_setprio(1); _Pragma("unroll") for (int m = 0; m < 4; ++m) _Pragma("unroll") for (int n = 0; n < 2; ++n) _Pragma("unroll") for (int k = 0; k < 2; ++k) \
;         acc[ai][bj][m][n] = __builtin_amdgcn_mfma_f32_16x16x32_bf16(Bt[n][k], At[m][k], acc[ai][bj][m][n], 0, 0, 0); __builtin_amdgcn_s_setprio(0); } while (0)
; #define PG8_WAIT_V(n) asm volatile("s_waitcnt vmcnt(" #n ")" ::: "memory")
; #define PG8_WAIT_L(n) asm volatile("s_waitcnt lgkmcnt(" #n ")" ::: "memory")
; #define PG8_BAR __builtin_amdgcn_s_barrier()
; #define PG8_SCHED __builtin_amdgcn_sched_barrier(0)
; template <class Epi, class Sched, bool ALIGN_EPI = false, bool SP2 = false>
; __device__ __forceinline__ void gemm_phase(PG8_LAS unsigned char* lds, const Gemm g, const Sched& S, const Epi& E, int wave_s) {
;     ...
;             PG8_LDB(B0, 0, 0); PG8_LDB(B1, 0, 1); PG8_SCHED; PG8_LDA(At, 0, 0); PG8_STAGE(PG8_SA(1, 1), a1 + hstep, voffA);
;             PG8_WAIT_V(8); PG8_WAIT_L(0); PG8_BAR; PG8_MMA(0, 0, At, B0); PG8_MMA(0, 1, At, B1); PG8_BAR; PG8_SCHED;
;             PG8_LDA(At, 0, 1); PG8_STAGE(PG8_SB(0, 0), b2, voffB); PG8_STAGE(PG8_SB(0, 1), b2 + hstep, voffB); PG8_STAGE(PG8_SA(0, 0), a2, voffA);
.LBB0_120:
	ds_read_b128 v[128:131], v187
	ds_read_b128 v[132:135], v187 offset:1024
	ds_read_b128 v[160:163], v187 offset:2048
	ds_read_b128 v[164:167], v187 offset:3072
	ds_read_b128 v[168:171], v188
	ds_read_b128 v[172:175], v188 offset:1024
	ds_read_b128 v[176:179], v188 offset:2048
	ds_read_b128 v[192:195], v188 offset:3072
	s_add_u32 s6, s4, 0xfffc0080
	s_addc_u32 s7, s5, -1
	s_cmp_eq_u32 s67, 12
	s_cselect_b32 s9, s3, s7
	s_cselect_b32 s8, s10, s6
	s_cselect_b32 s7, s11, s57
	s_cselect_b32 s6, s12, s47
	v_lshl_add_u64 v[180:181], s[4:5], 0, v[152:153]
	s_add_i32 m0, s65, 0xc000
	ds_read_b128 v[196:199], v189
	ds_read_b128 v[200:203], v189 offset:1024
	ds_read_b128 v[204:207], v189 offset:2048
	ds_read_b128 v[208:211], v189 offset:3072
	ds_read_b128 v[212:215], v189 offset:4096
	ds_read_b128 v[216:219], v189 offset:5120
	ds_read_b128 v[220:223], v189 offset:6144
	ds_read_b128 v[224:227], v189 offset:7168
	global_load_lds_dwordx4 v[180:181], off
	s_add_i32 m0, s65, 0xe000
	v_lshl_add_u64 v[180:181], s[4:5], 0, v[154:155]
	global_load_lds_dwordx4 v[180:181], off
	s_waitcnt vmcnt(8)
	s_waitcnt lgkmcnt(0)
	s_barrier
	s_setprio 1
	s_waitcnt lgkmcnt(0)
	v_mfma_f32_16x16x32_bf16 v[124:127], v[128:131], v[196:199], v[124:127]
	v_mfma_f32_16x16x32_bf16 v[120:123], v[160:163], v[196:199], v[120:123]
	v_mfma_f32_16x16x32_bf16 v[108:111], v[128:131], v[204:207], v[108:111]
	v_mfma_f32_16x16x32_bf16 v[104:107], v[160:163], v[204:207], v[104:107]
	v_mfma_f32_16x16x32_bf16 v[92:95], v[128:131], v[212:215], v[92:95]
	v_mfma_f32_16x16x32_bf16 v[88:91], v[160:163], v[212:215], v[88:91]
	v_mfma_f32_16x16x32_bf16 v[76:79], v[128:131], v[220:223], v[76:79]
	v_mfma_f32_16x16x32_bf16 v[72:75], v[160:163], v[220:223], v[72:75]
	v_mfma_f32_16x16x32_bf16 v[124:127], v[132:135], v[200:203], v[124:127]
	v_mfma_f32_16x16x32_bf16 v[120:123], v[164:167], v[200:203], v[120:123]
	v_mfma_f32_16x16x32_bf16 v[108:111], v[132:135], v[208:211], v[108:111]
	v_mfma_f32_16x16x32_bf16 v[104:107], v[164:167], v[208:211], v[104:107]
	v_mfma_f32_16x16x32_bf16 v[92:95], v[132:135], v[216:219], v[92:95]
	v_mfma_f32_16x16x32_bf16 v[88:91], v[164:167], v[216:219], v[88:91]
	v_mfma_f32_16x16x32_bf16 v[76:79], v[132:135], v[224:227], v[76:79]
	v_mfma_f32_16x16x32_bf16 v[72:75], v[164:167], v[224:227], v[72:75]
	s_setprio 0
	s_setprio 1
	v_mfma_f32_16x16x32_bf16 v[116:119], v[168:171], v[196:199], v[116:119]
	v_mfma_f32_16x16x32_bf16 v[112:115], v[176:179], v[196:199], v[112:115]
	v_mfma_f32_16x16x32_bf16 v[96:99], v[168:171], v[204:207], v[96:99]
	v_mfma_f32_16x16x32_bf16 v[100:103], v[176:179], v[204:207], v[100:103]
	v_mfma_f32_16x16x32_bf16 v[80:83], v[168:171], v[212:215], v[80:83]
	v_mfma_f32_16x16x32_bf16 v[84:87], v[176:179], v[212:215], v[84:87]
	v_mfma_f32_16x16x32_bf16 v[64:67], v[168:171], v[220:223], v[64:67]
	v_mfma_f32_16x16x32_bf16 v[68:71], v[176:179], v[220:223], v[68:71]
	v_mfma_f32_16x16x32_bf16 v[116:119], v[172:175], v[200:203], v[116:119]
	v_mfma_f32_16x16x32_bf16 v[112:115], v[192:195], v[200:203], v[112:115]
	v_mfma_f32_16x16x32_bf16 v[96:99], v[172:175], v[208:211], v[96:99]
	v_mfma_f32_16x16x32_bf16 v[100:103], v[192:195], v[208:211], v[100:103]
	v_mfma_f32_16x16x32_bf16 v[80:83], v[172:175], v[216:219], v[80:83]
	v_mfma_f32_16x16x32_bf16 v[84:87], v[192:195], v[216:219], v[84:87]
	v_mfma_f32_16x16x32_bf16 v[64:67], v[172:175], v[224:227], v[64:67]
	v_mfma_f32_16x16x32_bf16 v[68:71], v[192:195], v[224:227], v[68:71]
	s_setprio 0
	s_barrier
	s_add_i32 s58, s16, s59
	v_lshl_add_u64 v[180:181], s[6:7], 0, v[138:139]
	s_mov_b32 m0, s58
	ds_read_b128 v[196:199], v189 offset:16384
	ds_read_b128 v[200:203], v189 offset:17408
	ds_read_b128 v[204:207], v189 offset:18432
	ds_read_b128 v[208:211], v189 offset:19456
	ds_read_b128 v[212:215], v189 offset:20480
	ds_read_b128 v[216:219], v189 offset:21504
	ds_read_b128 v[220:223], v189 offset:22528
	ds_read_b128 v[224:227], v189 offset:23552
	global_load_lds_dwordx4 v[180:181], off
	s_add_i32 m0, s58, 0x2000
	s_add_u32 s76, s6, 0x40000
	v_lshl_add_u64 v[228:229], s[6:7], 0, v[142:143]
	s_addc_u32 s77, s7, 0
	s_add_i32 s58, s17, s59
	global_load_lds_dwordx4 v[228:229], off
	v_lshl_add_u64 v[230:231], s[76:77], 0, v[138:139]
	s_mov_b32 m0, s58
	v_lshl_add_u64 v[232:233], s[8:9], 0, v[140:141]
	global_load_lds_dwordx4 v[230:231], off
	s_add_i32 m0, s58, 0x2000
	v_lshl_add_u64 v[230:231], s[76:77], 0, v[142:143]
	global_load_lds_dwordx4 v[230:231], off
	s_mov_b32 m0, s65
	v_lshl_add_u64 v[230:231], s[8:9], 0, v[136:137]
	global_load_lds_dwordx4 v[230:231], off
	s_mov_b32 m0, s75
	s_nop 0
	global_load_lds_dwordx4 v[232:233], off
	s_waitcnt vmcnt(8)
	s_waitcnt lgkmcnt(0)
	s_barrier
; #define PG8_STAGE(bufoff, gbase, voff) do { _Pragma("unroll") for (int _i = 0; _i < 2; ++_i) \
;         __builtin_amdgcn_global_load_lds((const unsigned*)((const char*)(gbase) + (voff)[_i]), (PG8_LAS unsigned*)(lds + (bufoff) + ldsw + _i * 8192), 16, 0, 0); } while (0)
; #define PG8_LDA(dst, b, h) do { _Pragma("unroll") for (int m = 0; m < 4; ++m) _Pragma("unroll") for (int k = 0; k < 2; ++k) dst[m][k] = *(const PG8_LAS bf16x8*)(lds + PG8_SA(b, h) + aoff + m * 2048 + k * 1024); } while (0)
; #define PG8_LDB(dst, b, h) do { _Pragma("unroll") for (int n = 0; n < 2; ++n) _Pragma("unroll") for (int k = 0; k < 2; ++k) dst[n][k] = *(const PG8_LAS bf16x8*)(lds + PG8_SB(b, h) + boff + n * 2048 + k * 1024); } while (0)
; #define PG8_MMA(ai, bj, At, Bt) do { __builtin_amdgcn_s_setprio(1); _Pragma("unroll") for (int m = 0; m < 4; ++m) _Pragma("unroll") for (int n = 0; n < 2; ++n) _Pragma("unroll") for (int k = 0; k < 2; ++k) \
;         acc[ai][bj][m][n] = __builtin_amdgcn_mfma_f32_16x16x32_bf16(Bt[n][k], At[m][k], acc[ai][bj][m][n], 0, 0, 0); __builtin_amdgcn_s_setprio(0); } while (0)
; #define PG8_WAIT_V(n) asm volatile("s_waitcnt vmcnt(" #n ")" ::: "memory")
; #define PG8_WAIT_L(n) asm volatile("s_waitcnt lgkmcnt(" #n ")" ::: "memory")
; #define PG8_BAR __builtin_amdgcn_s_barrier()
; #define PG8_SCHED __builtin_amdgcn_sched_barrier(0)
; template <class Epi, class Sched, bool ALIGN_EPI = false, bool SP2 = false>
; __device__ __forceinline__ void gemm_phase(PG8_LAS unsigned char* lds, const Gemm g, const Sched& S, const Epi& E, int wave_s) {
;     ...
;             PG8_WAIT_V(8); PG8_WAIT_L(0); PG8_BAR; PG8_MMA(1, 0, At, B0); PG8_MMA(1, 1, At, B1); PG8_BAR; PG8_SCHED;
;             PG8_LDB(B0, 1, 0); PG8_LDB(B1, 1, 1); PG8_SCHED; PG8_LDA(At, 1, 0); PG8_STAGE(PG8_SA(0, 1), a2 + hstep, voffA);
;             PG8_WAIT_V(8); PG8_WAIT_L(0); PG8_BAR; PG8_MMA(0, 0, At, B0); PG8_MMA(0, 1, At, B1); PG8_BAR; PG8_SCHED;
	s_setprio 1
	s_waitcnt lgkmcnt(0)
	v_mfma_f32_16x16x32_bf16 v[60:63], v[128:131], v[196:199], v[60:63]
	v_mfma_f32_16x16x32_bf16 v[56:59], v[160:163], v[196:199], v[56:59]
	v_mfma_f32_16x16x32_bf16 v[44:47], v[128:131], v[204:207], v[44:47]
	v_mfma_f32_16x16x32_bf16 v[40:43], v[160:163], v[204:207], v[40:43]
	v_mfma_f32_16x16x32_bf16 v[28:31], v[128:131], v[212:215], v[28:31]
	v_mfma_f32_16x16x32_bf16 v[24:27], v[160:163], v[212:215], v[24:27]
	v_mfma_f32_16x16x32_bf16 v[12:15], v[128:131], v[220:223], v[12:15]
	v_mfma_f32_16x16x32_bf16 v[8:11], v[160:163], v[220:223], v[8:11]
	v_mfma_f32_16x16x32_bf16 v[60:63], v[132:135], v[200:203], v[60:63]
	v_mfma_f32_16x16x32_bf16 v[56:59], v[164:167], v[200:203], v[56:59]
	v_mfma_f32_16x16x32_bf16 v[44:47], v[132:135], v[208:211], v[44:47]
	v_mfma_f32_16x16x32_bf16 v[40:43], v[164:167], v[208:211], v[40:43]
	v_mfma_f32_16x16x32_bf16 v[28:31], v[132:135], v[216:219], v[28:31]
	v_mfma_f32_16x16x32_bf16 v[24:27], v[164:167], v[216:219], v[24:27]
	v_mfma_f32_16x16x32_bf16 v[12:15], v[132:135], v[224:227], v[12:15]
	v_mfma_f32_16x16x32_bf16 v[8:11], v[164:167], v[224:227], v[8:11]
	s_setprio 0
	s_setprio 1
	v_mfma_f32_16x16x32_bf16 v[48:51], v[168:171], v[196:199], v[48:51]
	v_mfma_f32_16x16x32_bf16 v[52:55], v[176:179], v[196:199], v[52:55]
	v_mfma_f32_16x16x32_bf16 v[32:35], v[168:171], v[204:207], v[32:35]
	v_mfma_f32_16x16x32_bf16 v[36:39], v[176:179], v[204:207], v[36:39]
	v_mfma_f32_16x16x32_bf16 v[16:19], v[168:171], v[212:215], v[16:19]
	v_mfma_f32_16x16x32_bf16 v[20:23], v[176:179], v[212:215], v[20:23]
	v_mfma_f32_16x16x32_bf16 v[0:3], v[168:171], v[220:223], v[0:3]
	v_mfma_f32_16x16x32_bf16 v[4:7], v[176:179], v[220:223], v[4:7]
	v_mfma_f32_16x16x32_bf16 v[48:51], v[172:175], v[200:203], v[48:51]
	v_mfma_f32_16x16x32_bf16 v[52:55], v[192:195], v[200:203], v[52:55]
	v_mfma_f32_16x16x32_bf16 v[32:35], v[172:175], v[208:211], v[32:35]
	v_mfma_f32_16x16x32_bf16 v[36:39], v[192:195], v[208:211], v[36:39]
	v_mfma_f32_16x16x32_bf16 v[16:19], v[172:175], v[216:219], v[16:19]
	v_mfma_f32_16x16x32_bf16 v[20:23], v[192:195], v[216:219], v[20:23]
	v_mfma_f32_16x16x32_bf16 v[0:3], v[172:175], v[224:227], v[0:3]
	v_mfma_f32_16x16x32_bf16 v[4:7], v[192:195], v[224:227], v[4:7]
	s_setprio 0
	s_barrier
	s_add_i32 s58, 0, 0x18000
	v_add_u32_e32 v144, s58, v184
	s_add_i32 s69, 0, 0x1c000
	ds_read_b128 v[128:131], v144
	ds_read_b128 v[132:135], v144 offset:1024
	ds_read_b128 v[160:163], v144 offset:2048
	ds_read_b128 v[164:167], v144 offset:3072
	v_add_u32_e32 v144, s69, v184
	ds_read_b128 v[168:171], v144
	ds_read_b128 v[172:175], v144 offset:1024
	ds_read_b128 v[176:179], v144 offset:2048
	ds_read_b128 v[192:195], v144 offset:3072
	s_add_u32 s8, s8, 0x40000
	s_addc_u32 s9, s9, 0
	s_mov_b32 m0, s90
	v_lshl_add_u64 v[234:235], s[8:9], 0, v[136:137]
	ds_read_b128 v[196:199], v189 offset:32768
	ds_read_b128 v[200:203], v189 offset:33792
	ds_read_b128 v[204:207], v189 offset:34816
	ds_read_b128 v[208:211], v189 offset:35840
	ds_read_b128 v[212:215], v189 offset:36864
	ds_read_b128 v[216:219], v189 offset:37888
	ds_read_b128 v[220:223], v189 offset:38912
	ds_read_b128 v[224:227], v189 offset:39936
	global_load_lds_dwordx4 v[234:235], off
	s_mov_b32 m0, s92
	v_lshl_add_u64 v[234:235], s[8:9], 0, v[140:141]
	global_load_lds_dwordx4 v[234:235], off
	s_waitcnt vmcnt(8)
	s_waitcnt lgkmcnt(0)
	s_barrier
	s_setprio 1
	s_waitcnt lgkmcnt(0)
	v_mfma_f32_16x16x32_bf16 v[124:127], v[128:131], v[196:199], v[124:127]
	v_mfma_f32_16x16x32_bf16 v[120:123], v[160:163], v[196:199], v[120:123]
	v_mfma_f32_16x16x32_bf16 v[108:111], v[128:131], v[204:207], v[108:111]
	v_mfma_f32_16x16x32_bf16 v[104:107], v[160:163], v[204:207], v[104:107]
	v_mfma_f32_16x16x32_bf16 v[92:95], v[128:131], v[212:215], v[92:95]
	v_mfma_f32_16x16x32_bf16 v[88:91], v[160:163], v[212:215], v[88:91]
	v_mfma_f32_16x16x32_bf16 v[76:79], v[128:131], v[220:223], v[76:79]
	v_mfma_f32_16x16x32_bf16 v[72:75], v[160:163], v[220:223], v[72:75]
	v_mfma_f32_16x16x32_bf16 v[124:127], v[132:135], v[200:203], v[124:127]
	v_mfma_f32_16x16x32_bf16 v[120:123], v[164:167], v[200:203], v[120:123]
	v_mfma_f32_16x16x32_bf16 v[108:111], v[132:135], v[208:211], v[108:111]
	v_mfma_f32_16x16x32_bf16 v[104:107], v[164:167], v[208:211], v[104:107]
	v_mfma_f32_16x16x32_bf16 v[92:95], v[132:135], v[216:219], v[92:95]
	v_mfma_f32_16x16x32_bf16 v[88:91], v[164:167], v[216:219], v[88:91]
	v_mfma_f32_16x16x32_bf16 v[76:79], v[132:135], v[224:227], v[76:79]
	v_mfma_f32_16x16x32_bf16 v[72:75], v[164:167], v[224:227], v[72:75]
	s_setprio 0
	s_setprio 1
	v_mfma_f32_16x16x32_bf16 v[116:119], v[168:171], v[196:199], v[116:119]
	v_mfma_f32_16x16x32_bf16 v[112:115], v[176:179], v[196:199], v[112:115]
	v_mfma_f32_16x16x32_bf16 v[96:99], v[168:171], v[204:207], v[96:99]
	v_mfma_f32_16x16x32_bf16 v[100:103], v[176:179], v[204:207], v[100:103]
	v_mfma_f32_16x16x32_bf16 v[80:83], v[168:171], v[212:215], v[80:83]
	v_mfma_f32_16x16x32_bf16 v[84:87], v[176:179], v[212:215], v[84:87]
	v_mfma_f32_16x16x32_bf16 v[64:67], v[168:171], v[220:223], v[64:67]
	v_mfma_f32_16x16x32_bf16 v[68:71], v[176:179], v[220:223], v[68:71]
	v_mfma_f32_16x16x32_bf16 v[116:119], v[172:175], v[200:203], v[116:119]
	v_mfma_f32_16x16x32_bf16 v[112:115], v[192:195], v[200:203], v[112:115]
	v_mfma_f32_16x16x32_bf16 v[96:99], v[172:175], v[208:211], v[96:99]
	v_mfma_f32_16x16x32_bf16 v[100:103], v[192:195], v[208:211], v[100:103]
	v_mfma_f32_16x16x32_bf16 v[80:83], v[172:175], v[216:219], v[80:83]
	v_mfma_f32_16x16x32_bf16 v[84:87], v[192:195], v[216:219], v[84:87]
	v_mfma_f32_16x16x32_bf16 v[64:67], v[172:175], v[224:227], v[64:67]
	v_mfma_f32_16x16x32_bf16 v[68:71], v[192:195], v[224:227], v[68:71]
	s_setprio 0
	s_barrier
; #define PG8_STAGE(bufoff, gbase, voff) do { _Pragma("unroll") for (int _i = 0; _i < 2; ++_i) \
;         __builtin_amdgcn_global_load_lds((const unsigned*)((const char*)(gbase) + (voff)[_i]), (PG8_LAS unsigned*)(lds + (bufoff) + ldsw + _i * 8192), 16, 0, 0); } while (0)
; #define PG8_LDA(dst, b, h) do { _Pragma("unroll") for (int m = 0; m < 4; ++m) _Pragma("unroll") for (int k = 0; k < 2; ++k) dst[m][k] = *(const PG8_LAS bf16x8*)(lds + PG8_SA(b, h) + aoff + m * 2048 + k * 1024); } while (0)
; #define PG8_MMA(ai, bj, At, Bt) do { __builtin_amdgcn_s_setprio(1); _Pragma("unroll") for (int m = 0; m < 4; ++m) _Pragma("unroll") for (int n = 0; n < 2; ++n) _Pragma("unroll") for (int k = 0; k < 2; ++k) \
;         acc[ai][bj][m][n] = __builtin_amdgcn_mfma_f32_16x16x32_bf16(Bt[n][k], At[m][k], acc[ai][bj][m][n], 0, 0, 0); __builtin_amdgcn_s_setprio(0); } while (0)
; #define PG8_WAIT_V(n) asm volatile("s_waitcnt vmcnt(" #n ")" ::: "memory")
; #define PG8_WAIT_L(n) asm volatile("s_waitcnt lgkmcnt(" #n ")" ::: "memory")
; #define PG8_BAR __builtin_amdgcn_s_barrier()
; #define PG8_SCHED __builtin_amdgcn_sched_barrier(0)
; template <class Epi, class Sched, bool ALIGN_EPI = false, bool SP2 = false>
; __device__ __forceinline__ void gemm_phase(PG8_LAS unsigned char* lds, const Gemm g, const Sched& S, const Epi& E, int wave_s) {
;     ...
;             PG8_LDA(At, 1, 1); PG8_STAGE(PG8_SB(1, 0), b3, voffB); PG8_STAGE(PG8_SB(1, 1), b3 + hstep, voffB); PG8_STAGE(PG8_SA(1, 0), a3, voffA);
;             PG8_WAIT_V(8); PG8_WAIT_L(0); PG8_BAR; PG8_MMA(1, 0, At, B0); PG8_MMA(1, 1, At, B1); PG8_BAR; PG8_SCHED;
	s_add_i32 s8, s58, s59
	v_lshl_add_u64 v[180:181], v[180:181], 0, s[30:31]
	s_mov_b32 m0, s8
	ds_read_b128 v[196:199], v189 offset:49152
	ds_read_b128 v[200:203], v189 offset:50176
	ds_read_b128 v[204:207], v189 offset:51200
	ds_read_b128 v[208:211], v189 offset:52224
	ds_read_b128 v[212:215], v189 offset:53248
	ds_read_b128 v[216:219], v189 offset:54272
	ds_read_b128 v[220:223], v189 offset:55296
	ds_read_b128 v[224:227], v189 offset:56320
	global_load_lds_dwordx4 v[180:181], off
	s_add_i32 m0, s8, 0x2000
	s_add_u32 s6, s6, 0x40080
	v_lshl_add_u64 v[180:181], v[228:229], 0, s[30:31]
	s_addc_u32 s7, s7, 0
	s_add_i32 s8, s69, s59
	global_load_lds_dwordx4 v[180:181], off
	s_mov_b32 m0, s8
	v_lshl_add_u64 v[180:181], s[6:7], 0, v[138:139]
	global_load_lds_dwordx4 v[180:181], off
	s_add_i32 m0, s8, 0x2000
	v_lshl_add_u64 v[180:181], s[6:7], 0, v[142:143]
	global_load_lds_dwordx4 v[180:181], off
	s_mov_b32 m0, s94
	v_lshl_add_u64 v[180:181], v[230:231], 0, s[30:31]
	global_load_lds_dwordx4 v[180:181], off
	s_mov_b32 m0, s95
	v_lshl_add_u64 v[180:181], v[232:233], 0, s[30:31]
	global_load_lds_dwordx4 v[180:181], off
	s_waitcnt vmcnt(8)
	s_waitcnt lgkmcnt(0)
	s_barrier
	s_setprio 1
	s_waitcnt lgkmcnt(0)
	v_mfma_f32_16x16x32_bf16 v[60:63], v[128:131], v[196:199], v[60:63]
	v_mfma_f32_16x16x32_bf16 v[56:59], v[160:163], v[196:199], v[56:59]
	v_mfma_f32_16x16x32_bf16 v[44:47], v[128:131], v[204:207], v[44:47]
	v_mfma_f32_16x16x32_bf16 v[40:43], v[160:163], v[204:207], v[40:43]
	v_mfma_f32_16x16x32_bf16 v[28:31], v[128:131], v[212:215], v[28:31]
	v_mfma_f32_16x16x32_bf16 v[24:27], v[160:163], v[212:215], v[24:27]
	v_mfma_f32_16x16x32_bf16 v[12:15], v[128:131], v[220:223], v[12:15]
	v_mfma_f32_16x16x32_bf16 v[8:11], v[160:163], v[220:223], v[8:11]
	v_mfma_f32_16x16x32_bf16 v[60:63], v[132:135], v[200:203], v[60:63]
	v_mfma_f32_16x16x32_bf16 v[56:59], v[164:167], v[200:203], v[56:59]
	v_mfma_f32_16x16x32_bf16 v[44:47], v[132:135], v[208:211], v[44:47]
	v_mfma_f32_16x16x32_bf16 v[40:43], v[164:167], v[208:211], v[40:43]
	v_mfma_f32_16x16x32_bf16 v[28:31], v[132:135], v[216:219], v[28:31]
	v_mfma_f32_16x16x32_bf16 v[24:27], v[164:167], v[216:219], v[24:27]
	v_mfma_f32_16x16x32_bf16 v[12:15], v[132:135], v[224:227], v[12:15]
	v_mfma_f32_16x16x32_bf16 v[8:11], v[164:167], v[224:227], v[8:11]
	s_setprio 0
	s_setprio 1
	v_mfma_f32_16x16x32_bf16 v[48:51], v[168:171], v[196:199], v[48:51]
	v_mfma_f32_16x16x32_bf16 v[52:55], v[176:179], v[196:199], v[52:55]
	v_mfma_f32_16x16x32_bf16 v[32:35], v[168:171], v[204:207], v[32:35]
	v_mfma_f32_16x16x32_bf16 v[36:39], v[176:179], v[204:207], v[36:39]
	v_mfma_f32_16x16x32_bf16 v[16:19], v[168:171], v[212:215], v[16:19]
	v_mfma_f32_16x16x32_bf16 v[20:23], v[176:179], v[212:215], v[20:23]
	v_mfma_f32_16x16x32_bf16 v[0:3], v[168:171], v[220:223], v[0:3]
	v_mfma_f32_16x16x32_bf16 v[4:7], v[176:179], v[220:223], v[4:7]
	v_mfma_f32_16x16x32_bf16 v[48:51], v[172:175], v[200:203], v[48:51]
	v_mfma_f32_16x16x32_bf16 v[52:55], v[192:195], v[200:203], v[52:55]
	v_mfma_f32_16x16x32_bf16 v[32:35], v[172:175], v[208:211], v[32:35]
	v_mfma_f32_16x16x32_bf16 v[36:39], v[192:195], v[208:211], v[36:39]
	v_mfma_f32_16x16x32_bf16 v[16:19], v[172:175], v[216:219], v[16:19]
	v_mfma_f32_16x16x32_bf16 v[20:23], v[192:195], v[216:219], v[20:23]
	v_mfma_f32_16x16x32_bf16 v[0:3], v[172:175], v[224:227], v[0:3]
	v_mfma_f32_16x16x32_bf16 v[4:7], v[192:195], v[224:227], v[4:7]
	s_setprio 0
	s_barrier
	s_add_i32 s67, s67, 2
	s_add_u32 s4, s4, 0x100
	s_addc_u32 s5, s5, 0
	s_add_u32 s47, s47, 0x100
	s_addc_u32 s57, s57, 0
	s_cmp_gt_u32 s67, 13
	s_cbranch_scc0 .LBB0_120
	s_and_b64 vcc, exec, s[78:79]
	s_cbranch_vccz .LBB0_123
	s_barrier

; #define PG8_STAGE(bufoff, gbase, voff) do { _Pragma("unroll") for (int _i = 0; _i < 2; ++_i) \
;         __builtin_amdgcn_global_load_lds((const unsigned*)((const char*)(gbase) + (voff)[_i]), (PG8_LAS unsigned*)(lds + (bufoff) + ldsw + _i * 8192), 16, 0, 0); } while (0)
; #define PG8_LDA(dst, b, h) do { _Pragma("unroll") for (int m = 0; m < 4; ++m) _Pragma("unroll") for (int k = 0; k < 2; ++k) dst[m][k] = *(const PG8_LAS bf16x8*)(lds + PG8_SA(b, h) + aoff + m * 2048 + k * 1024); } while (0)
; #define PG8_LDB(dst, b, h) do { _Pragma("unroll") for (int n = 0; n < 2; ++n) _Pragma("unroll") for (int k = 0; k < 2; ++k) dst[n][k] = *(const PG8_LAS bf16x8*)(lds + PG8_SB(b, h) + boff + n * 2048 + k * 1024); } while (0)
; #define PG8_MMA(ai, bj, At, Bt) do { __builtin_amdgcn_s_setprio(1); _Pragma("unroll") for (int m = 0; m < 4; ++m) _Pragma("unroll") for (int n = 0; n < 2; ++n) _Pragma("unroll") for (int k = 0; k < 2; ++k) \
;         acc[ai][bj][m][n] = __builtin_amdgcn_mfma_f32_16x16x32_bf16(Bt[n][k], At[m][k], acc[ai][bj][m][n], 0, 0, 0); __builtin_amdgcn_s_setprio(0); } while (0)
; #define PG8_WAIT_V(n) asm volatile("s_waitcnt vmcnt(" #n ")" ::: "memory")
; #define PG8_WAIT_L(n) asm volatile("s_waitcnt lgkmcnt(" #n ")" ::: "memory")
; #define PG8_BAR __builtin_amdgcn_s_barrier()
; #define PG8_SCHED __builtin_amdgcn_sched_barrier(0)
; template <class Epi, class Sched, bool ALIGN_EPI = false, bool SP2 = false>
; __device__ __forceinline__ void gemm_phase(PG8_LAS unsigned char* lds, const Gemm g, const Sched& S, const Epi& E, int wave_s) {
;     ...
;             PG8_LDB(B0, 0, 0); PG8_LDB(B1, 0, 1); PG8_SCHED; PG8_LDA(At, 0, 0); PG8_STAGE(PG8_SA(1, 1), a1 + hstep, voffA);
;             PG8_WAIT_V(8); PG8_WAIT_L(0); PG8_BAR; PG8_MMA(0, 0, At, B0); PG8_MMA(0, 1, At, B1); PG8_BAR; PG8_SCHED;
;             PG8_LDA(At, 0, 1); PG8_STAGE(PG8_SB(0, 0), b2, voffB); PG8_STAGE(PG8_SB(0, 1), b2 + hstep, voffB); PG8_STAGE(PG8_SA(0, 0), a2, voffA);
.LBB0_1026:
	ds_read_b128 v[146:149], v153
	ds_read_b128 v[158:161], v153 offset:1024
	ds_read_b128 v[162:165], v153 offset:2048
	ds_read_b128 v[166:169], v153 offset:3072
	ds_read_b128 v[170:173], v154
	ds_read_b128 v[174:177], v154 offset:1024
	ds_read_b128 v[178:181], v154 offset:2048
	ds_read_b128 v[182:185], v154 offset:3072
	s_add_u32 s40, s26, 0xfffc0080
	s_addc_u32 s41, s27, -1
	s_cmp_eq_u32 s73, 12
	s_cselect_b32 s43, s19, s41
	s_cselect_b32 s42, s69, s40
	s_cselect_b32 s41, s17, s72
	s_cselect_b32 s40, s70, s71
	v_lshl_add_u64 v[210:211], s[26:27], 0, v[138:139]
	s_add_i32 m0, s25, 0xc000
	ds_read_b128 v[186:189], v155
	ds_read_b128 v[190:193], v155 offset:1024
	ds_read_b128 v[194:197], v155 offset:2048
	ds_read_b128 v[198:201], v155 offset:3072
	ds_read_b128 v[202:205], v155 offset:4096
	ds_read_b128 v[206:209], v155 offset:5120
	ds_read_b128 v[214:217], v155 offset:6144
	ds_read_b128 v[218:221], v155 offset:7168
	global_load_lds_dwordx4 v[210:211], off
	s_add_i32 m0, s25, 0xe000
	v_lshl_add_u64 v[210:211], s[26:27], 0, v[140:141]
	global_load_lds_dwordx4 v[210:211], off
	s_waitcnt vmcnt(8)
	s_waitcnt lgkmcnt(0)
	s_barrier
	s_setprio 1
	s_waitcnt lgkmcnt(0)
	v_mfma_f32_16x16x32_bf16 v[124:127], v[146:149], v[186:189], v[124:127]
	v_mfma_f32_16x16x32_bf16 v[120:123], v[162:165], v[186:189], v[120:123]
	v_mfma_f32_16x16x32_bf16 v[108:111], v[146:149], v[194:197], v[108:111]
	v_mfma_f32_16x16x32_bf16 v[104:107], v[162:165], v[194:197], v[104:107]
	v_mfma_f32_16x16x32_bf16 v[92:95], v[146:149], v[202:205], v[92:95]
	v_mfma_f32_16x16x32_bf16 v[88:91], v[162:165], v[202:205], v[88:91]
	v_mfma_f32_16x16x32_bf16 v[76:79], v[146:149], v[214:217], v[76:79]
	v_mfma_f32_16x16x32_bf16 v[72:75], v[162:165], v[214:217], v[72:75]
	v_mfma_f32_16x16x32_bf16 v[124:127], v[158:161], v[190:193], v[124:127]
	v_mfma_f32_16x16x32_bf16 v[120:123], v[166:169], v[190:193], v[120:123]
	v_mfma_f32_16x16x32_bf16 v[108:111], v[158:161], v[198:201], v[108:111]
	v_mfma_f32_16x16x32_bf16 v[104:107], v[166:169], v[198:201], v[104:107]
	v_mfma_f32_16x16x32_bf16 v[92:95], v[158:161], v[206:209], v[92:95]
	v_mfma_f32_16x16x32_bf16 v[88:91], v[166:169], v[206:209], v[88:91]
	v_mfma_f32_16x16x32_bf16 v[76:79], v[158:161], v[218:221], v[76:79]
	v_mfma_f32_16x16x32_bf16 v[72:75], v[166:169], v[218:221], v[72:75]
	s_setprio 0
	s_setprio 1
	v_mfma_f32_16x16x32_bf16 v[116:119], v[170:173], v[186:189], v[116:119]
	v_mfma_f32_16x16x32_bf16 v[112:115], v[178:181], v[186:189], v[112:115]
	v_mfma_f32_16x16x32_bf16 v[100:103], v[170:173], v[194:197], v[100:103]
	v_mfma_f32_16x16x32_bf16 v[96:99], v[178:181], v[194:197], v[96:99]
	v_mfma_f32_16x16x32_bf16 v[84:87], v[170:173], v[202:205], v[84:87]
	v_mfma_f32_16x16x32_bf16 v[80:83], v[178:181], v[202:205], v[80:83]
	v_mfma_f32_16x16x32_bf16 v[68:71], v[170:173], v[214:217], v[68:71]
	v_mfma_f32_16x16x32_bf16 v[64:67], v[178:181], v[214:217], v[64:67]
	v_mfma_f32_16x16x32_bf16 v[116:119], v[174:177], v[190:193], v[116:119]
	v_mfma_f32_16x16x32_bf16 v[112:115], v[182:185], v[190:193], v[112:115]
	v_mfma_f32_16x16x32_bf16 v[100:103], v[174:177], v[198:201], v[100:103]
	v_mfma_f32_16x16x32_bf16 v[96:99], v[182:185], v[198:201], v[96:99]
	v_mfma_f32_16x16x32_bf16 v[84:87], v[174:177], v[206:209], v[84:87]
	v_mfma_f32_16x16x32_bf16 v[80:83], v[182:185], v[206:209], v[80:83]
	v_mfma_f32_16x16x32_bf16 v[68:71], v[174:177], v[218:221], v[68:71]
	v_mfma_f32_16x16x32_bf16 v[64:67], v[182:185], v[218:221], v[64:67]
	s_setprio 0
	s_barrier
	s_add_i32 s74, s62, s49
	v_lshl_add_u64 v[210:211], s[40:41], 0, v[130:131]
	s_mov_b32 m0, s74
	ds_read_b128 v[186:189], v155 offset:16384
	ds_read_b128 v[190:193], v155 offset:17408
	ds_read_b128 v[194:197], v155 offset:18432
	ds_read_b128 v[198:201], v155 offset:19456
	ds_read_b128 v[202:205], v155 offset:20480
	ds_read_b128 v[206:209], v155 offset:21504
	ds_read_b128 v[214:217], v155 offset:22528
	ds_read_b128 v[218:221], v155 offset:23552
	global_load_lds_dwordx4 v[210:211], off
	s_add_i32 m0, s74, 0x2000
	s_add_u32 s74, s40, 0x40000
	v_lshl_add_u64 v[222:223], s[40:41], 0, v[134:135]
	s_addc_u32 s75, s41, 0
	s_add_i32 s76, s63, s49
	global_load_lds_dwordx4 v[222:223], off
	v_lshl_add_u64 v[224:225], s[74:75], 0, v[130:131]
	s_mov_b32 m0, s76
	v_lshl_add_u64 v[226:227], s[42:43], 0, v[132:133]
	global_load_lds_dwordx4 v[224:225], off
	s_add_i32 m0, s76, 0x2000
	v_lshl_add_u64 v[224:225], s[74:75], 0, v[134:135]
	global_load_lds_dwordx4 v[224:225], off
	s_mov_b32 m0, s25
	v_lshl_add_u64 v[224:225], s[42:43], 0, v[128:129]
	global_load_lds_dwordx4 v[224:225], off
	s_mov_b32 m0, s50
	s_nop 0
	global_load_lds_dwordx4 v[226:227], off
	s_waitcnt vmcnt(8)
	s_waitcnt lgkmcnt(0)
	s_barrier
; #define PG8_STAGE(bufoff, gbase, voff) do { _Pragma("unroll") for (int _i = 0; _i < 2; ++_i) \
;         __builtin_amdgcn_global_load_lds((const unsigned*)((const char*)(gbase) + (voff)[_i]), (PG8_LAS unsigned*)(lds + (bufoff) + ldsw + _i * 8192), 16, 0, 0); } while (0)
; #define PG8_LDA(dst, b, h) do { _Pragma("unroll") for (int m = 0; m < 4; ++m) _Pragma("unroll") for (int k = 0; k < 2; ++k) dst[m][k] = *(const PG8_LAS bf16x8*)(lds + PG8_SA(b, h) + aoff + m * 2048 + k * 1024); } while (0)
; #define PG8_LDB(dst, b, h) do { _Pragma("unroll") for (int n = 0; n < 2; ++n) _Pragma("unroll") for (int k = 0; k < 2; ++k) dst[n][k] = *(const PG8_LAS bf16x8*)(lds + PG8_SB(b, h) + boff + n * 2048 + k * 1024); } while (0)
; #define PG8_MMA(ai, bj, At, Bt) do { __builtin_amdgcn_s_setprio(1); _Pragma("unroll") for (int m = 0; m < 4; ++m) _Pragma("unroll") for (int n = 0; n < 2; ++n) _Pragma("unroll") for (int k = 0; k < 2; ++k) \
;         acc[ai][bj][m][n] = __builtin_amdgcn_mfma_f32_16x16x32_bf16(Bt[n][k], At[m][k], acc[ai][bj][m][n], 0, 0, 0); __builtin_amdgcn_s_setprio(0); } while (0)
; #define PG8_WAIT_V(n) asm volatile("s_waitcnt vmcnt(" #n ")" ::: "memory")
; #define PG8_WAIT_L(n) asm volatile("s_waitcnt lgkmcnt(" #n ")" ::: "memory")
; #define PG8_BAR __builtin_amdgcn_s_barrier()
; #define PG8_SCHED __builtin_amdgcn_sched_barrier(0)
; template <class Epi, class Sched, bool ALIGN_EPI = false, bool SP2 = false>
; __device__ __forceinline__ void gemm_phase(PG8_LAS unsigned char* lds, const Gemm g, const Sched& S, const Epi& E, int wave_s) {
;     ...
;             PG8_WAIT_V(8); PG8_WAIT_L(0); PG8_BAR; PG8_MMA(1, 0, At, B0); PG8_MMA(1, 1, At, B1); PG8_BAR; PG8_SCHED;
;             PG8_LDB(B0, 1, 0); PG8_LDB(B1, 1, 1); PG8_SCHED; PG8_LDA(At, 1, 0); PG8_STAGE(PG8_SA(0, 1), a2 + hstep, voffA);
;             PG8_WAIT_V(8); PG8_WAIT_L(0); PG8_BAR; PG8_MMA(0, 0, At, B0); PG8_MMA(0, 1, At, B1); PG8_BAR; PG8_SCHED;
	s_setprio 1
	s_waitcnt lgkmcnt(0)
	v_mfma_f32_16x16x32_bf16 v[60:63], v[146:149], v[186:189], v[60:63]
	v_mfma_f32_16x16x32_bf16 v[56:59], v[162:165], v[186:189], v[56:59]
	v_mfma_f32_16x16x32_bf16 v[44:47], v[146:149], v[194:197], v[44:47]
	v_mfma_f32_16x16x32_bf16 v[40:43], v[162:165], v[194:197], v[40:43]
	v_mfma_f32_16x16x32_bf16 v[28:31], v[146:149], v[202:205], v[28:31]
	v_mfma_f32_16x16x32_bf16 v[24:27], v[162:165], v[202:205], v[24:27]
	v_mfma_f32_16x16x32_bf16 v[12:15], v[146:149], v[214:217], v[12:15]
	v_mfma_f32_16x16x32_bf16 v[8:11], v[162:165], v[214:217], v[8:11]
	v_mfma_f32_16x16x32_bf16 v[60:63], v[158:161], v[190:193], v[60:63]
	v_mfma_f32_16x16x32_bf16 v[56:59], v[166:169], v[190:193], v[56:59]
	v_mfma_f32_16x16x32_bf16 v[44:47], v[158:161], v[198:201], v[44:47]
	v_mfma_f32_16x16x32_bf16 v[40:43], v[166:169], v[198:201], v[40:43]
	v_mfma_f32_16x16x32_bf16 v[28:31], v[158:161], v[206:209], v[28:31]
	v_mfma_f32_16x16x32_bf16 v[24:27], v[166:169], v[206:209], v[24:27]
	v_mfma_f32_16x16x32_bf16 v[12:15], v[158:161], v[218:221], v[12:15]
	v_mfma_f32_16x16x32_bf16 v[8:11], v[166:169], v[218:221], v[8:11]
	s_setprio 0
	s_setprio 1
	v_mfma_f32_16x16x32_bf16 v[52:55], v[170:173], v[186:189], v[52:55]
	v_mfma_f32_16x16x32_bf16 v[48:51], v[178:181], v[186:189], v[48:51]
	v_mfma_f32_16x16x32_bf16 v[36:39], v[170:173], v[194:197], v[36:39]
	v_mfma_f32_16x16x32_bf16 v[32:35], v[178:181], v[194:197], v[32:35]
	v_mfma_f32_16x16x32_bf16 v[20:23], v[170:173], v[202:205], v[20:23]
	v_mfma_f32_16x16x32_bf16 v[16:19], v[178:181], v[202:205], v[16:19]
	v_mfma_f32_16x16x32_bf16 v[4:7], v[170:173], v[214:217], v[4:7]
	v_mfma_f32_16x16x32_bf16 v[0:3], v[178:181], v[214:217], v[0:3]
	v_mfma_f32_16x16x32_bf16 v[52:55], v[174:177], v[190:193], v[52:55]
	v_mfma_f32_16x16x32_bf16 v[48:51], v[182:185], v[190:193], v[48:51]
	v_mfma_f32_16x16x32_bf16 v[36:39], v[174:177], v[198:201], v[36:39]
	v_mfma_f32_16x16x32_bf16 v[32:35], v[182:185], v[198:201], v[32:35]
	v_mfma_f32_16x16x32_bf16 v[20:23], v[174:177], v[206:209], v[20:23]
	v_mfma_f32_16x16x32_bf16 v[16:19], v[182:185], v[206:209], v[16:19]
	v_mfma_f32_16x16x32_bf16 v[4:7], v[174:177], v[218:221], v[4:7]
	v_mfma_f32_16x16x32_bf16 v[0:3], v[182:185], v[218:221], v[0:3]
	s_setprio 0
	s_barrier
	s_add_i32 s74, 0, 0x18000
	v_add_u32_e32 v136, s74, v151
	s_add_i32 s75, 0, 0x1c000
	ds_read_b128 v[146:149], v136
	ds_read_b128 v[158:161], v136 offset:1024
	ds_read_b128 v[162:165], v136 offset:2048
	ds_read_b128 v[166:169], v136 offset:3072
	v_add_u32_e32 v136, s75, v151
	ds_read_b128 v[170:173], v136
	ds_read_b128 v[174:177], v136 offset:1024
	ds_read_b128 v[178:181], v136 offset:2048
	ds_read_b128 v[182:185], v136 offset:3072
	s_add_u32 s42, s42, 0x40000
	s_addc_u32 s43, s43, 0
	s_mov_b32 m0, s51
	v_lshl_add_u64 v[228:229], s[42:43], 0, v[128:129]
	ds_read_b128 v[186:189], v155 offset:32768
	ds_read_b128 v[190:193], v155 offset:33792
	ds_read_b128 v[194:197], v155 offset:34816
	ds_read_b128 v[198:201], v155 offset:35840
	ds_read_b128 v[202:205], v155 offset:36864
	ds_read_b128 v[206:209], v155 offset:37888
	ds_read_b128 v[214:217], v155 offset:38912
	ds_read_b128 v[218:221], v155 offset:39936
	global_load_lds_dwordx4 v[228:229], off
	s_mov_b32 m0, s56
	v_lshl_add_u64 v[228:229], s[42:43], 0, v[132:133]
	global_load_lds_dwordx4 v[228:229], off
	s_waitcnt vmcnt(8)
	s_waitcnt lgkmcnt(0)
	s_barrier
	s_setprio 1
	s_waitcnt lgkmcnt(0)
	v_mfma_f32_16x16x32_bf16 v[124:127], v[146:149], v[186:189], v[124:127]
	v_mfma_f32_16x16x32_bf16 v[120:123], v[162:165], v[186:189], v[120:123]
	v_mfma_f32_16x16x32_bf16 v[108:111], v[146:149], v[194:197], v[108:111]
	v_mfma_f32_16x16x32_bf16 v[104:107], v[162:165], v[194:197], v[104:107]
	v_mfma_f32_16x16x32_bf16 v[92:95], v[146:149], v[202:205], v[92:95]
	v_mfma_f32_16x16x32_bf16 v[88:91], v[162:165], v[202:205], v[88:91]
	v_mfma_f32_16x16x32_bf16 v[76:79], v[146:149], v[214:217], v[76:79]
	v_mfma_f32_16x16x32_bf16 v[72:75], v[162:165], v[214:217], v[72:75]
	v_mfma_f32_16x16x32_bf16 v[124:127], v[158:161], v[190:193], v[124:127]
	v_mfma_f32_16x16x32_bf16 v[120:123], v[166:169], v[190:193], v[120:123]
	v_mfma_f32_16x16x32_bf16 v[108:111], v[158:161], v[198:201], v[108:111]
	v_mfma_f32_16x16x32_bf16 v[104:107], v[166:169], v[198:201], v[104:107]
	v_mfma_f32_16x16x32_bf16 v[92:95], v[158:161], v[206:209], v[92:95]
	v_mfma_f32_16x16x32_bf16 v[88:91], v[166:169], v[206:209], v[88:91]
	v_mfma_f32_16x16x32_bf16 v[76:79], v[158:161], v[218:221], v[76:79]
	v_mfma_f32_16x16x32_bf16 v[72:75], v[166:169], v[218:221], v[72:75]
	s_setprio 0
	s_setprio 1
	v_mfma_f32_16x16x32_bf16 v[116:119], v[170:173], v[186:189], v[116:119]
	v_mfma_f32_16x16x32_bf16 v[112:115], v[178:181], v[186:189], v[112:115]
	v_mfma_f32_16x16x32_bf16 v[100:103], v[170:173], v[194:197], v[100:103]
	v_mfma_f32_16x16x32_bf16 v[96:99], v[178:181], v[194:197], v[96:99]
	v_mfma_f32_16x16x32_bf16 v[84:87], v[170:173], v[202:205], v[84:87]
	v_mfma_f32_16x16x32_bf16 v[80:83], v[178:181], v[202:205], v[80:83]
	v_mfma_f32_16x16x32_bf16 v[68:71], v[170:173], v[214:217], v[68:71]
	v_mfma_f32_16x16x32_bf16 v[64:67], v[178:181], v[214:217], v[64:67]
	v_mfma_f32_16x16x32_bf16 v[116:119], v[174:177], v[190:193], v[116:119]
	v_mfma_f32_16x16x32_bf16 v[112:115], v[182:185], v[190:193], v[112:115]
	v_mfma_f32_16x16x32_bf16 v[100:103], v[174:177], v[198:201], v[100:103]
	v_mfma_f32_16x16x32_bf16 v[96:99], v[182:185], v[198:201], v[96:99]
	v_mfma_f32_16x16x32_bf16 v[84:87], v[174:177], v[206:209], v[84:87]
	v_mfma_f32_16x16x32_bf16 v[80:83], v[182:185], v[206:209], v[80:83]
	v_mfma_f32_16x16x32_bf16 v[68:71], v[174:177], v[218:221], v[68:71]
	v_mfma_f32_16x16x32_bf16 v[64:67], v[182:185], v[218:221], v[64:67]
	s_setprio 0
	s_barrier
; #define PG8_STAGE(bufoff, gbase, voff) do { _Pragma("unroll") for (int _i = 0; _i < 2; ++_i) \
;         __builtin_amdgcn_global_load_lds((const unsigned*)((const char*)(gbase) + (voff)[_i]), (PG8_LAS unsigned*)(lds + (bufoff) + ldsw + _i * 8192), 16, 0, 0); } while (0)
; #define PG8_LDA(dst, b, h) do { _Pragma("unroll") for (int m = 0; m < 4; ++m) _Pragma("unroll") for (int k = 0; k < 2; ++k) dst[m][k] = *(const PG8_LAS bf16x8*)(lds + PG8_SA(b, h) + aoff + m * 2048 + k * 1024); } while (0)
; #define PG8_MMA(ai, bj, At, Bt) do { __builtin_amdgcn_s_setprio(1); _Pragma("unroll") for (int m = 0; m < 4; ++m) _Pragma("unroll") for (int n = 0; n < 2; ++n) _Pragma("unroll") for (int k = 0; k < 2; ++k) \
;         acc[ai][bj][m][n] = __builtin_amdgcn_mfma_f32_16x16x32_bf16(Bt[n][k], At[m][k], acc[ai][bj][m][n], 0, 0, 0); __builtin_amdgcn_s_setprio(0); } while (0)
; #define PG8_WAIT_V(n) asm volatile("s_waitcnt vmcnt(" #n ")" ::: "memory")
; #define PG8_WAIT_L(n) asm volatile("s_waitcnt lgkmcnt(" #n ")" ::: "memory")
; #define PG8_BAR __builtin_amdgcn_s_barrier()
; #define PG8_SCHED __builtin_amdgcn_sched_barrier(0)
; template <class Epi, class Sched, bool ALIGN_EPI = false, bool SP2 = false>
; __device__ __forceinline__ void gemm_phase(PG8_LAS unsigned char* lds, const Gemm g, const Sched& S, const Epi& E, int wave_s) {
;     ...
;             PG8_LDA(At, 1, 1); PG8_STAGE(PG8_SB(1, 0), b3, voffB); PG8_STAGE(PG8_SB(1, 1), b3 + hstep, voffB); PG8_STAGE(PG8_SA(1, 0), a3, voffA);
;             PG8_WAIT_V(8); PG8_WAIT_L(0); PG8_BAR; PG8_MMA(1, 0, At, B0); PG8_MMA(1, 1, At, B1); PG8_BAR; PG8_SCHED;
	s_add_i32 s42, s74, s49
	v_lshl_add_u64 v[210:211], v[210:211], 0, s[10:11]
	s_mov_b32 m0, s42
	ds_read_b128 v[186:189], v155 offset:49152
	ds_read_b128 v[190:193], v155 offset:50176
	ds_read_b128 v[194:197], v155 offset:51200
	ds_read_b128 v[198:201], v155 offset:52224
	ds_read_b128 v[202:205], v155 offset:53248
	ds_read_b128 v[206:209], v155 offset:54272
	ds_read_b128 v[214:217], v155 offset:55296
	ds_read_b128 v[218:221], v155 offset:56320
	global_load_lds_dwordx4 v[210:211], off
	s_add_i32 m0, s42, 0x2000
	s_add_u32 s40, s40, 0x40080
	v_lshl_add_u64 v[210:211], v[222:223], 0, s[10:11]
	s_addc_u32 s41, s41, 0
	s_add_i32 s42, s75, s49
	global_load_lds_dwordx4 v[210:211], off
	s_mov_b32 m0, s42
	v_lshl_add_u64 v[210:211], s[40:41], 0, v[130:131]
	global_load_lds_dwordx4 v[210:211], off
	s_add_i32 m0, s42, 0x2000
	v_lshl_add_u64 v[210:211], s[40:41], 0, v[134:135]
	global_load_lds_dwordx4 v[210:211], off
	s_mov_b32 m0, s58
	v_lshl_add_u64 v[210:211], v[224:225], 0, s[10:11]
	global_load_lds_dwordx4 v[210:211], off
	s_mov_b32 m0, s59
	v_lshl_add_u64 v[210:211], v[226:227], 0, s[10:11]
	global_load_lds_dwordx4 v[210:211], off
	s_waitcnt vmcnt(8)
	s_waitcnt lgkmcnt(0)
	s_barrier
	s_setprio 1
	s_waitcnt lgkmcnt(0)
	v_mfma_f32_16x16x32_bf16 v[60:63], v[146:149], v[186:189], v[60:63]
	v_mfma_f32_16x16x32_bf16 v[56:59], v[162:165], v[186:189], v[56:59]
	v_mfma_f32_16x16x32_bf16 v[44:47], v[146:149], v[194:197], v[44:47]
	v_mfma_f32_16x16x32_bf16 v[40:43], v[162:165], v[194:197], v[40:43]
	v_mfma_f32_16x16x32_bf16 v[28:31], v[146:149], v[202:205], v[28:31]
	v_mfma_f32_16x16x32_bf16 v[24:27], v[162:165], v[202:205], v[24:27]
	v_mfma_f32_16x16x32_bf16 v[12:15], v[146:149], v[214:217], v[12:15]
	v_mfma_f32_16x16x32_bf16 v[8:11], v[162:165], v[214:217], v[8:11]
	v_mfma_f32_16x16x32_bf16 v[60:63], v[158:161], v[190:193], v[60:63]
	v_mfma_f32_16x16x32_bf16 v[56:59], v[166:169], v[190:193], v[56:59]
	v_mfma_f32_16x16x32_bf16 v[44:47], v[158:161], v[198:201], v[44:47]
	v_mfma_f32_16x16x32_bf16 v[40:43], v[166:169], v[198:201], v[40:43]
	v_mfma_f32_16x16x32_bf16 v[28:31], v[158:161], v[206:209], v[28:31]
	v_mfma_f32_16x16x32_bf16 v[24:27], v[166:169], v[206:209], v[24:27]
	v_mfma_f32_16x16x32_bf16 v[12:15], v[158:161], v[218:221], v[12:15]
	v_mfma_f32_16x16x32_bf16 v[8:11], v[166:169], v[218:221], v[8:11]
	s_setprio 0
	s_setprio 1
	v_mfma_f32_16x16x32_bf16 v[52:55], v[170:173], v[186:189], v[52:55]
	v_mfma_f32_16x16x32_bf16 v[48:51], v[178:181], v[186:189], v[48:51]
	v_mfma_f32_16x16x32_bf16 v[36:39], v[170:173], v[194:197], v[36:39]
	v_mfma_f32_16x16x32_bf16 v[32:35], v[178:181], v[194:197], v[32:35]
	v_mfma_f32_16x16x32_bf16 v[20:23], v[170:173], v[202:205], v[20:23]
	v_mfma_f32_16x16x32_bf16 v[16:19], v[178:181], v[202:205], v[16:19]
	v_mfma_f32_16x16x32_bf16 v[4:7], v[170:173], v[214:217], v[4:7]
	v_mfma_f32_16x16x32_bf16 v[0:3], v[178:181], v[214:217], v[0:3]
	v_mfma_f32_16x16x32_bf16 v[52:55], v[174:177], v[190:193], v[52:55]
	v_mfma_f32_16x16x32_bf16 v[48:51], v[182:185], v[190:193], v[48:51]
	v_mfma_f32_16x16x32_bf16 v[36:39], v[174:177], v[198:201], v[36:39]
	v_mfma_f32_16x16x32_bf16 v[32:35], v[182:185], v[198:201], v[32:35]
	v_mfma_f32_16x16x32_bf16 v[20:23], v[174:177], v[206:209], v[20:23]
	v_mfma_f32_16x16x32_bf16 v[16:19], v[182:185], v[206:209], v[16:19]
	v_mfma_f32_16x16x32_bf16 v[4:7], v[174:177], v[218:221], v[4:7]
	v_mfma_f32_16x16x32_bf16 v[0:3], v[182:185], v[218:221], v[0:3]
	s_setprio 0
	s_barrier
	s_add_i32 s73, s73, 2
	s_add_u32 s26, s26, 0x100
	s_addc_u32 s27, s27, 0
	s_add_u32 s71, s71, 0x100
	s_addc_u32 s72, s72, 0
	s_cmp_gt_u32 s73, 13
	s_cbranch_scc0 .LBB0_1026
	s_and_b64 vcc, exec, s[12:13]
	s_cbranch_vccz .LBB0_1029
	s_barrier

; #define PG8_STAGE(bufoff, gbase, voff) do { _Pragma("unroll") for (int _i = 0; _i < 2; ++_i) \
;         __builtin_amdgcn_global_load_lds((const unsigned*)((const char*)(gbase) + (voff)[_i]), (PG8_LAS unsigned*)(lds + (bufoff) + ldsw + _i * 8192), 16, 0, 0); } while (0)
; #define PG8_LDA(dst, b, h) do { _Pragma("unroll") for (int m = 0; m < 4; ++m) _Pragma("unroll") for (int k = 0; k < 2; ++k) dst[m][k] = *(const PG8_LAS bf16x8*)(lds + PG8_SA(b, h) + aoff + m * 2048 + k * 1024); } while (0)
; #define PG8_LDB(dst, b, h) do { _Pragma("unroll") for (int n = 0; n < 2; ++n) _Pragma("unroll") for (int k = 0; k < 2; ++k) dst[n][k] = *(const PG8_LAS bf16x8*)(lds + PG8_SB(b, h) + boff + n * 2048 + k * 1024); } while (0)
; #define PG8_MMA(ai, bj, At, Bt) do { __builtin_amdgcn_s_setprio(1); _Pragma("unroll") for (int m = 0; m < 4; ++m) _Pragma("unroll") for (int n = 0; n < 2; ++n) _Pragma("unroll") for (int k = 0; k < 2; ++k) \
;         acc[ai][bj][m][n] = __builtin_amdgcn_mfma_f32_16x16x32_bf16(Bt[n][k], At[m][k], acc[ai][bj][m][n], 0, 0, 0); __builtin_amdgcn_s_setprio(0); } while (0)
; #define PG8_WAIT_V(n) asm volatile("s_waitcnt vmcnt(" #n ")" ::: "memory")
; #define PG8_WAIT_L(n) asm volatile("s_waitcnt lgkmcnt(" #n ")" ::: "memory")
; #define PG8_BAR __builtin_amdgcn_s_barrier()
; #define PG8_SCHED __builtin_amdgcn_sched_barrier(0)
; template <class Epi, class Sched, bool ALIGN_EPI = false, bool SP2 = false>
; __device__ __forceinline__ void gemm_phase(PG8_LAS unsigned char* lds, const Gemm g, const Sched& S, const Epi& E, int wave_s) {
;     ...
;             PG8_LDB(B0, 0, 0); PG8_LDB(B1, 0, 1); PG8_SCHED; PG8_LDA(At, 0, 0); PG8_STAGE(PG8_SA(1, 1), a1 + hstep, voffA);
;             PG8_WAIT_V(8); PG8_WAIT_L(0); PG8_BAR; PG8_MMA(0, 0, At, B0); PG8_MMA(0, 1, At, B1); PG8_BAR; PG8_SCHED;
;             PG8_LDA(At, 0, 1); PG8_STAGE(PG8_SB(0, 0), b2, voffB); PG8_STAGE(PG8_SB(0, 1), b2 + hstep, voffB); PG8_STAGE(PG8_SA(0, 0), a2, voffA);
.LBB0_1053:
	ds_read_b128 v[146:149], v153
	ds_read_b128 v[158:161], v153 offset:1024
	ds_read_b128 v[162:165], v153 offset:2048
	ds_read_b128 v[166:169], v153 offset:3072
	ds_read_b128 v[170:173], v154
	ds_read_b128 v[174:177], v154 offset:1024
	ds_read_b128 v[178:181], v154 offset:2048
	ds_read_b128 v[182:185], v154 offset:3072
	s_add_u32 s26, s24, 0xfffc0080
	s_addc_u32 s27, s25, -1
	s_cmp_eq_u32 s70, 12
	s_cselect_b32 s41, s17, s27
	s_cselect_b32 s40, s66, s26
	s_cselect_b32 s27, s13, s69
	s_cselect_b32 s26, s67, s68
	v_lshl_add_u64 v[210:211], s[24:25], 0, v[138:139]
	s_add_i32 m0, s23, 0xc000
	ds_read_b128 v[186:189], v155
	ds_read_b128 v[190:193], v155 offset:1024
	ds_read_b128 v[194:197], v155 offset:2048
	ds_read_b128 v[198:201], v155 offset:3072
	ds_read_b128 v[202:205], v155 offset:4096
	ds_read_b128 v[206:209], v155 offset:5120
	ds_read_b128 v[214:217], v155 offset:6144
	ds_read_b128 v[218:221], v155 offset:7168
	global_load_lds_dwordx4 v[210:211], off
	s_add_i32 m0, s23, 0xe000
	v_lshl_add_u64 v[210:211], s[24:25], 0, v[140:141]
	global_load_lds_dwordx4 v[210:211], off
	s_waitcnt vmcnt(8)
	s_waitcnt lgkmcnt(0)
	s_barrier
	s_setprio 1
	s_waitcnt lgkmcnt(0)
	v_mfma_f32_16x16x32_bf16 v[124:127], v[146:149], v[186:189], v[124:127]
	v_mfma_f32_16x16x32_bf16 v[120:123], v[162:165], v[186:189], v[120:123]
	v_mfma_f32_16x16x32_bf16 v[108:111], v[146:149], v[194:197], v[108:111]
	v_mfma_f32_16x16x32_bf16 v[104:107], v[162:165], v[194:197], v[104:107]
	v_mfma_f32_16x16x32_bf16 v[92:95], v[146:149], v[202:205], v[92:95]
	v_mfma_f32_16x16x32_bf16 v[88:91], v[162:165], v[202:205], v[88:91]
	v_mfma_f32_16x16x32_bf16 v[76:79], v[146:149], v[214:217], v[76:79]
	v_mfma_f32_16x16x32_bf16 v[72:75], v[162:165], v[214:217], v[72:75]
	v_mfma_f32_16x16x32_bf16 v[124:127], v[158:161], v[190:193], v[124:127]
	v_mfma_f32_16x16x32_bf16 v[120:123], v[166:169], v[190:193], v[120:123]
	v_mfma_f32_16x16x32_bf16 v[108:111], v[158:161], v[198:201], v[108:111]
	v_mfma_f32_16x16x32_bf16 v[104:107], v[166:169], v[198:201], v[104:107]
	v_mfma_f32_16x16x32_bf16 v[92:95], v[158:161], v[206:209], v[92:95]
	v_mfma_f32_16x16x32_bf16 v[88:91], v[166:169], v[206:209], v[88:91]
	v_mfma_f32_16x16x32_bf16 v[76:79], v[158:161], v[218:221], v[76:79]
	v_mfma_f32_16x16x32_bf16 v[72:75], v[166:169], v[218:221], v[72:75]
	s_setprio 0
	s_setprio 1
	v_mfma_f32_16x16x32_bf16 v[116:119], v[170:173], v[186:189], v[116:119]
	v_mfma_f32_16x16x32_bf16 v[112:115], v[178:181], v[186:189], v[112:115]
	v_mfma_f32_16x16x32_bf16 v[100:103], v[170:173], v[194:197], v[100:103]
	v_mfma_f32_16x16x32_bf16 v[96:99], v[178:181], v[194:197], v[96:99]
	v_mfma_f32_16x16x32_bf16 v[84:87], v[170:173], v[202:205], v[84:87]
	v_mfma_f32_16x16x32_bf16 v[80:83], v[178:181], v[202:205], v[80:83]
	v_mfma_f32_16x16x32_bf16 v[68:71], v[170:173], v[214:217], v[68:71]
	v_mfma_f32_16x16x32_bf16 v[64:67], v[178:181], v[214:217], v[64:67]
	v_mfma_f32_16x16x32_bf16 v[116:119], v[174:177], v[190:193], v[116:119]
	v_mfma_f32_16x16x32_bf16 v[112:115], v[182:185], v[190:193], v[112:115]
	v_mfma_f32_16x16x32_bf16 v[100:103], v[174:177], v[198:201], v[100:103]
	v_mfma_f32_16x16x32_bf16 v[96:99], v[182:185], v[198:201], v[96:99]
	v_mfma_f32_16x16x32_bf16 v[84:87], v[174:177], v[206:209], v[84:87]
	v_mfma_f32_16x16x32_bf16 v[80:83], v[182:185], v[206:209], v[80:83]
	v_mfma_f32_16x16x32_bf16 v[68:71], v[174:177], v[218:221], v[68:71]
	v_mfma_f32_16x16x32_bf16 v[64:67], v[182:185], v[218:221], v[64:67]
	s_setprio 0
	s_barrier
	s_add_i32 s71, s59, s46
	v_lshl_add_u64 v[210:211], s[26:27], 0, v[130:131]
	s_mov_b32 m0, s71
	ds_read_b128 v[186:189], v155 offset:16384
	ds_read_b128 v[190:193], v155 offset:17408
	ds_read_b128 v[194:197], v155 offset:18432
	ds_read_b128 v[198:201], v155 offset:19456
	ds_read_b128 v[202:205], v155 offset:20480
	ds_read_b128 v[206:209], v155 offset:21504
	ds_read_b128 v[214:217], v155 offset:22528
	ds_read_b128 v[218:221], v155 offset:23552
	global_load_lds_dwordx4 v[210:211], off
	s_add_i32 m0, s71, 0x2000
	s_add_u32 s72, s26, 0x40000
	v_lshl_add_u64 v[222:223], s[26:27], 0, v[134:135]
	s_addc_u32 s73, s27, 0
	s_add_i32 s71, s60, s46
	global_load_lds_dwordx4 v[222:223], off
	v_lshl_add_u64 v[224:225], s[72:73], 0, v[130:131]
	s_mov_b32 m0, s71
	v_lshl_add_u64 v[226:227], s[40:41], 0, v[132:133]
	global_load_lds_dwordx4 v[224:225], off
	s_add_i32 m0, s71, 0x2000
	v_lshl_add_u64 v[224:225], s[72:73], 0, v[134:135]
	global_load_lds_dwordx4 v[224:225], off
	s_mov_b32 m0, s23
	v_lshl_add_u64 v[224:225], s[40:41], 0, v[128:129]
	global_load_lds_dwordx4 v[224:225], off
	s_mov_b32 m0, s47
	s_nop 0
	global_load_lds_dwordx4 v[226:227], off
	s_waitcnt vmcnt(8)
	s_waitcnt lgkmcnt(0)
	s_barrier
; #define PG8_STAGE(bufoff, gbase, voff) do { _Pragma("unroll") for (int _i = 0; _i < 2; ++_i) \
;         __builtin_amdgcn_global_load_lds((const unsigned*)((const char*)(gbase) + (voff)[_i]), (PG8_LAS unsigned*)(lds + (bufoff) + ldsw + _i * 8192), 16, 0, 0); } while (0)
; #define PG8_LDA(dst, b, h) do { _Pragma("unroll") for (int m = 0; m < 4; ++m) _Pragma("unroll") for (int k = 0; k < 2; ++k) dst[m][k] = *(const PG8_LAS bf16x8*)(lds + PG8_SA(b, h) + aoff + m * 2048 + k * 1024); } while (0)
; #define PG8_LDB(dst, b, h) do { _Pragma("unroll") for (int n = 0; n < 2; ++n) _Pragma("unroll") for (int k = 0; k < 2; ++k) dst[n][k] = *(const PG8_LAS bf16x8*)(lds + PG8_SB(b, h) + boff + n * 2048 + k * 1024); } while (0)
; #define PG8_MMA(ai, bj, At, Bt) do { __builtin_amdgcn_s_setprio(1); _Pragma("unroll") for (int m = 0; m < 4; ++m) _Pragma("unroll") for (int n = 0; n < 2; ++n) _Pragma("unroll") for (int k = 0; k < 2; ++k) \
;         acc[ai][bj][m][n] = __builtin_amdgcn_mfma_f32_16x16x32_bf16(Bt[n][k], At[m][k], acc[ai][bj][m][n], 0, 0, 0); __builtin_amdgcn_s_setprio(0); } while (0)
; #define PG8_WAIT_V(n) asm volatile("s_waitcnt vmcnt(" #n ")" ::: "memory")
; #define PG8_WAIT_L(n) asm volatile("s_waitcnt lgkmcnt(" #n ")" ::: "memory")
; #define PG8_BAR __builtin_amdgcn_s_barrier()
; #define PG8_SCHED __builtin_amdgcn_sched_barrier(0)
; template <class Epi, class Sched, bool ALIGN_EPI = false, bool SP2 = false>
; __device__ __forceinline__ void gemm_phase(PG8_LAS unsigned char* lds, const Gemm g, const Sched& S, const Epi& E, int wave_s) {
;     ...
;             PG8_WAIT_V(8); PG8_WAIT_L(0); PG8_BAR; PG8_MMA(1, 0, At, B0); PG8_MMA(1, 1, At, B1); PG8_BAR; PG8_SCHED;
;             PG8_LDB(B0, 1, 0); PG8_LDB(B1, 1, 1); PG8_SCHED; PG8_LDA(At, 1, 0); PG8_STAGE(PG8_SA(0, 1), a2 + hstep, voffA);
;             PG8_WAIT_V(8); PG8_WAIT_L(0); PG8_BAR; PG8_MMA(0, 0, At, B0); PG8_MMA(0, 1, At, B1); PG8_BAR; PG8_SCHED;
	s_setprio 1
	s_waitcnt lgkmcnt(0)
	v_mfma_f32_16x16x32_bf16 v[60:63], v[146:149], v[186:189], v[60:63]
	v_mfma_f32_16x16x32_bf16 v[56:59], v[162:165], v[186:189], v[56:59]
	v_mfma_f32_16x16x32_bf16 v[44:47], v[146:149], v[194:197], v[44:47]
	v_mfma_f32_16x16x32_bf16 v[40:43], v[162:165], v[194:197], v[40:43]
	v_mfma_f32_16x16x32_bf16 v[28:31], v[146:149], v[202:205], v[28:31]
	v_mfma_f32_16x16x32_bf16 v[24:27], v[162:165], v[202:205], v[24:27]
	v_mfma_f32_16x16x32_bf16 v[12:15], v[146:149], v[214:217], v[12:15]
	v_mfma_f32_16x16x32_bf16 v[8:11], v[162:165], v[214:217], v[8:11]
	v_mfma_f32_16x16x32_bf16 v[60:63], v[158:161], v[190:193], v[60:63]
	v_mfma_f32_16x16x32_bf16 v[56:59], v[166:169], v[190:193], v[56:59]
	v_mfma_f32_16x16x32_bf16 v[44:47], v[158:161], v[198:201], v[44:47]
	v_mfma_f32_16x16x32_bf16 v[40:43], v[166:169], v[198:201], v[40:43]
	v_mfma_f32_16x16x32_bf16 v[28:31], v[158:161], v[206:209], v[28:31]
	v_mfma_f32_16x16x32_bf16 v[24:27], v[166:169], v[206:209], v[24:27]
	v_mfma_f32_16x16x32_bf16 v[12:15], v[158:161], v[218:221], v[12:15]
	v_mfma_f32_16x16x32_bf16 v[8:11], v[166:169], v[218:221], v[8:11]
	s_setprio 0
	s_setprio 1
	v_mfma_f32_16x16x32_bf16 v[52:55], v[170:173], v[186:189], v[52:55]
	v_mfma_f32_16x16x32_bf16 v[48:51], v[178:181], v[186:189], v[48:51]
	v_mfma_f32_16x16x32_bf16 v[36:39], v[170:173], v[194:197], v[36:39]
	v_mfma_f32_16x16x32_bf16 v[32:35], v[178:181], v[194:197], v[32:35]
	v_mfma_f32_16x16x32_bf16 v[20:23], v[170:173], v[202:205], v[20:23]
	v_mfma_f32_16x16x32_bf16 v[16:19], v[178:181], v[202:205], v[16:19]
	v_mfma_f32_16x16x32_bf16 v[4:7], v[170:173], v[214:217], v[4:7]
	v_mfma_f32_16x16x32_bf16 v[0:3], v[178:181], v[214:217], v[0:3]
	v_mfma_f32_16x16x32_bf16 v[52:55], v[174:177], v[190:193], v[52:55]
	v_mfma_f32_16x16x32_bf16 v[48:51], v[182:185], v[190:193], v[48:51]
	v_mfma_f32_16x16x32_bf16 v[36:39], v[174:177], v[198:201], v[36:39]
	v_mfma_f32_16x16x32_bf16 v[32:35], v[182:185], v[198:201], v[32:35]
	v_mfma_f32_16x16x32_bf16 v[20:23], v[174:177], v[206:209], v[20:23]
	v_mfma_f32_16x16x32_bf16 v[16:19], v[182:185], v[206:209], v[16:19]
	v_mfma_f32_16x16x32_bf16 v[4:7], v[174:177], v[218:221], v[4:7]
	v_mfma_f32_16x16x32_bf16 v[0:3], v[182:185], v[218:221], v[0:3]
	s_setprio 0
	s_barrier
	s_add_i32 s71, 0, 0x18000
	v_add_u32_e32 v136, s71, v151
	s_add_i32 s72, 0, 0x1c000
	ds_read_b128 v[146:149], v136
	ds_read_b128 v[158:161], v136 offset:1024
	ds_read_b128 v[162:165], v136 offset:2048
	ds_read_b128 v[166:169], v136 offset:3072
	v_add_u32_e32 v136, s72, v151
	ds_read_b128 v[170:173], v136
	ds_read_b128 v[174:177], v136 offset:1024
	ds_read_b128 v[178:181], v136 offset:2048
	ds_read_b128 v[182:185], v136 offset:3072
	s_add_u32 s40, s40, 0x40000
	s_addc_u32 s41, s41, 0
	s_mov_b32 m0, s48
	v_lshl_add_u64 v[228:229], s[40:41], 0, v[128:129]
	ds_read_b128 v[186:189], v155 offset:32768
	ds_read_b128 v[190:193], v155 offset:33792
	ds_read_b128 v[194:197], v155 offset:34816
	ds_read_b128 v[198:201], v155 offset:35840
	ds_read_b128 v[202:205], v155 offset:36864
	ds_read_b128 v[206:209], v155 offset:37888
	ds_read_b128 v[214:217], v155 offset:38912
	ds_read_b128 v[218:221], v155 offset:39936
	global_load_lds_dwordx4 v[228:229], off
	s_mov_b32 m0, s49
	v_lshl_add_u64 v[228:229], s[40:41], 0, v[132:133]
	global_load_lds_dwordx4 v[228:229], off
	s_waitcnt vmcnt(8)
	s_waitcnt lgkmcnt(0)
	s_barrier
	s_setprio 1
	s_waitcnt lgkmcnt(0)
	v_mfma_f32_16x16x32_bf16 v[124:127], v[146:149], v[186:189], v[124:127]
	v_mfma_f32_16x16x32_bf16 v[120:123], v[162:165], v[186:189], v[120:123]
	v_mfma_f32_16x16x32_bf16 v[108:111], v[146:149], v[194:197], v[108:111]
	v_mfma_f32_16x16x32_bf16 v[104:107], v[162:165], v[194:197], v[104:107]
	v_mfma_f32_16x16x32_bf16 v[92:95], v[146:149], v[202:205], v[92:95]
	v_mfma_f32_16x16x32_bf16 v[88:91], v[162:165], v[202:205], v[88:91]
	v_mfma_f32_16x16x32_bf16 v[76:79], v[146:149], v[214:217], v[76:79]
	v_mfma_f32_16x16x32_bf16 v[72:75], v[162:165], v[214:217], v[72:75]
	v_mfma_f32_16x16x32_bf16 v[124:127], v[158:161], v[190:193], v[124:127]
	v_mfma_f32_16x16x32_bf16 v[120:123], v[166:169], v[190:193], v[120:123]
	v_mfma_f32_16x16x32_bf16 v[108:111], v[158:161], v[198:201], v[108:111]
	v_mfma_f32_16x16x32_bf16 v[104:107], v[166:169], v[198:201], v[104:107]
	v_mfma_f32_16x16x32_bf16 v[92:95], v[158:161], v[206:209], v[92:95]
	v_mfma_f32_16x16x32_bf16 v[88:91], v[166:169], v[206:209], v[88:91]
	v_mfma_f32_16x16x32_bf16 v[76:79], v[158:161], v[218:221], v[76:79]
	v_mfma_f32_16x16x32_bf16 v[72:75], v[166:169], v[218:221], v[72:75]
	s_setprio 0
	s_setprio 1
	v_mfma_f32_16x16x32_bf16 v[116:119], v[170:173], v[186:189], v[116:119]
	v_mfma_f32_16x16x32_bf16 v[112:115], v[178:181], v[186:189], v[112:115]
	v_mfma_f32_16x16x32_bf16 v[100:103], v[170:173], v[194:197], v[100:103]
	v_mfma_f32_16x16x32_bf16 v[96:99], v[178:181], v[194:197], v[96:99]
	v_mfma_f32_16x16x32_bf16 v[84:87], v[170:173], v[202:205], v[84:87]
	v_mfma_f32_16x16x32_bf16 v[80:83], v[178:181], v[202:205], v[80:83]
	v_mfma_f32_16x16x32_bf16 v[68:71], v[170:173], v[214:217], v[68:71]
	v_mfma_f32_16x16x32_bf16 v[64:67], v[178:181], v[214:217], v[64:67]
	v_mfma_f32_16x16x32_bf16 v[116:119], v[174:177], v[190:193], v[116:119]
	v_mfma_f32_16x16x32_bf16 v[112:115], v[182:185], v[190:193], v[112:115]
	v_mfma_f32_16x16x32_bf16 v[100:103], v[174:177], v[198:201], v[100:103]
	v_mfma_f32_16x16x32_bf16 v[96:99], v[182:185], v[198:201], v[96:99]
	v_mfma_f32_16x16x32_bf16 v[84:87], v[174:177], v[206:209], v[84:87]
	v_mfma_f32_16x16x32_bf16 v[80:83], v[182:185], v[206:209], v[80:83]
	v_mfma_f32_16x16x32_bf16 v[68:71], v[174:177], v[218:221], v[68:71]
	v_mfma_f32_16x16x32_bf16 v[64:67], v[182:185], v[218:221], v[64:67]
	s_setprio 0
	s_barrier
; #define PG8_STAGE(bufoff, gbase, voff) do { _Pragma("unroll") for (int _i = 0; _i < 2; ++_i) \
;         __builtin_amdgcn_global_load_lds((const unsigned*)((const char*)(gbase) + (voff)[_i]), (PG8_LAS unsigned*)(lds + (bufoff) + ldsw + _i * 8192), 16, 0, 0); } while (0)
; #define PG8_LDA(dst, b, h) do { _Pragma("unroll") for (int m = 0; m < 4; ++m) _Pragma("unroll") for (int k = 0; k < 2; ++k) dst[m][k] = *(const PG8_LAS bf16x8*)(lds + PG8_SA(b, h) + aoff + m * 2048 + k * 1024); } while (0)
; #define PG8_MMA(ai, bj, At, Bt) do { __builtin_amdgcn_s_setprio(1); _Pragma("unroll") for (int m = 0; m < 4; ++m) _Pragma("unroll") for (int n = 0; n < 2; ++n) _Pragma("unroll") for (int k = 0; k < 2; ++k) \
;         acc[ai][bj][m][n] = __builtin_amdgcn_mfma_f32_16x16x32_bf16(Bt[n][k], At[m][k], acc[ai][bj][m][n], 0, 0, 0); __builtin_amdgcn_s_setprio(0); } while (0)
; #define PG8_WAIT_V(n) asm volatile("s_waitcnt vmcnt(" #n ")" ::: "memory")
; #define PG8_WAIT_L(n) asm volatile("s_waitcnt lgkmcnt(" #n ")" ::: "memory")
; #define PG8_BAR __builtin_amdgcn_s_barrier()
; #define PG8_SCHED __builtin_amdgcn_sched_barrier(0)
; template <class Epi, class Sched, bool ALIGN_EPI = false, bool SP2 = false>
; __device__ __forceinline__ void gemm_phase(PG8_LAS unsigned char* lds, const Gemm g, const Sched& S, const Epi& E, int wave_s) {
;     ...
;             PG8_LDA(At, 1, 1); PG8_STAGE(PG8_SB(1, 0), b3, voffB); PG8_STAGE(PG8_SB(1, 1), b3 + hstep, voffB); PG8_STAGE(PG8_SA(1, 0), a3, voffA);
;             PG8_WAIT_V(8); PG8_WAIT_L(0); PG8_BAR; PG8_MMA(1, 0, At, B0); PG8_MMA(1, 1, At, B1); PG8_BAR; PG8_SCHED;
	s_add_i32 s40, s71, s46
	v_lshl_add_u64 v[210:211], v[210:211], 0, s[8:9]
	s_mov_b32 m0, s40
	ds_read_b128 v[186:189], v155 offset:49152
	ds_read_b128 v[190:193], v155 offset:50176
	ds_read_b128 v[194:197], v155 offset:51200
	ds_read_b128 v[198:201], v155 offset:52224
	ds_read_b128 v[202:205], v155 offset:53248
	ds_read_b128 v[206:209], v155 offset:54272
	ds_read_b128 v[214:217], v155 offset:55296
	ds_read_b128 v[218:221], v155 offset:56320
	global_load_lds_dwordx4 v[210:211], off
	s_add_i32 m0, s40, 0x2000
	s_add_u32 s26, s26, 0x40080
	v_lshl_add_u64 v[210:211], v[222:223], 0, s[8:9]
	s_addc_u32 s27, s27, 0
	s_add_i32 s40, s72, s46
	global_load_lds_dwordx4 v[210:211], off
	s_mov_b32 m0, s40
	v_lshl_add_u64 v[210:211], s[26:27], 0, v[130:131]
	global_load_lds_dwordx4 v[210:211], off
	s_add_i32 m0, s40, 0x2000
	v_lshl_add_u64 v[210:211], s[26:27], 0, v[134:135]
	global_load_lds_dwordx4 v[210:211], off
	s_mov_b32 m0, s51
	v_lshl_add_u64 v[210:211], v[224:225], 0, s[8:9]
	global_load_lds_dwordx4 v[210:211], off
	s_mov_b32 m0, s56
	v_lshl_add_u64 v[210:211], v[226:227], 0, s[8:9]
	global_load_lds_dwordx4 v[210:211], off
	s_waitcnt vmcnt(8)
	s_waitcnt lgkmcnt(0)
	s_barrier
	s_setprio 1
	s_waitcnt lgkmcnt(0)
	v_mfma_f32_16x16x32_bf16 v[60:63], v[146:149], v[186:189], v[60:63]
	v_mfma_f32_16x16x32_bf16 v[56:59], v[162:165], v[186:189], v[56:59]
	v_mfma_f32_16x16x32_bf16 v[44:47], v[146:149], v[194:197], v[44:47]
	v_mfma_f32_16x16x32_bf16 v[40:43], v[162:165], v[194:197], v[40:43]
	v_mfma_f32_16x16x32_bf16 v[28:31], v[146:149], v[202:205], v[28:31]
	v_mfma_f32_16x16x32_bf16 v[24:27], v[162:165], v[202:205], v[24:27]
	v_mfma_f32_16x16x32_bf16 v[12:15], v[146:149], v[214:217], v[12:15]
	v_mfma_f32_16x16x32_bf16 v[8:11], v[162:165], v[214:217], v[8:11]
	v_mfma_f32_16x16x32_bf16 v[60:63], v[158:161], v[190:193], v[60:63]
	v_mfma_f32_16x16x32_bf16 v[56:59], v[166:169], v[190:193], v[56:59]
	v_mfma_f32_16x16x32_bf16 v[44:47], v[158:161], v[198:201], v[44:47]
	v_mfma_f32_16x16x32_bf16 v[40:43], v[166:169], v[198:201], v[40:43]
	v_mfma_f32_16x16x32_bf16 v[28:31], v[158:161], v[206:209], v[28:31]
	v_mfma_f32_16x16x32_bf16 v[24:27], v[166:169], v[206:209], v[24:27]
	v_mfma_f32_16x16x32_bf16 v[12:15], v[158:161], v[218:221], v[12:15]
	v_mfma_f32_16x16x32_bf16 v[8:11], v[166:169], v[218:221], v[8:11]
	s_setprio 0
	s_setprio 1
	v_mfma_f32_16x16x32_bf16 v[52:55], v[170:173], v[186:189], v[52:55]
	v_mfma_f32_16x16x32_bf16 v[48:51], v[178:181], v[186:189], v[48:51]
	v_mfma_f32_16x16x32_bf16 v[36:39], v[170:173], v[194:197], v[36:39]
	v_mfma_f32_16x16x32_bf16 v[32:35], v[178:181], v[194:197], v[32:35]
	v_mfma_f32_16x16x32_bf16 v[20:23], v[170:173], v[202:205], v[20:23]
	v_mfma_f32_16x16x32_bf16 v[16:19], v[178:181], v[202:205], v[16:19]
	v_mfma_f32_16x16x32_bf16 v[4:7], v[170:173], v[214:217], v[4:7]
	v_mfma_f32_16x16x32_bf16 v[0:3], v[178:181], v[214:217], v[0:3]
	v_mfma_f32_16x16x32_bf16 v[52:55], v[174:177], v[190:193], v[52:55]
	v_mfma_f32_16x16x32_bf16 v[48:51], v[182:185], v[190:193], v[48:51]
	v_mfma_f32_16x16x32_bf16 v[36:39], v[174:177], v[198:201], v[36:39]
	v_mfma_f32_16x16x32_bf16 v[32:35], v[182:185], v[198:201], v[32:35]
	v_mfma_f32_16x16x32_bf16 v[20:23], v[174:177], v[206:209], v[20:23]
	v_mfma_f32_16x16x32_bf16 v[16:19], v[182:185], v[206:209], v[16:19]
	v_mfma_f32_16x16x32_bf16 v[4:7], v[174:177], v[218:221], v[4:7]
	v_mfma_f32_16x16x32_bf16 v[0:3], v[182:185], v[218:221], v[0:3]
	s_setprio 0
	s_barrier
	s_add_i32 s70, s70, 2
	s_add_u32 s24, s24, 0x100
	s_addc_u32 s25, s25, 0
	s_add_u32 s68, s68, 0x100
	s_addc_u32 s69, s69, 0
	s_cmp_gt_u32 s70, 13
	s_cbranch_scc0 .LBB0_1053
	s_and_b64 vcc, exec, s[10:11]
	s_cbranch_vccz .LBB0_1056
	s_barrier

; #define PG8_STAGE(bufoff, gbase, voff) do { _Pragma("unroll") for (int _i = 0; _i < 2; ++_i) \
;         __builtin_amdgcn_global_load_lds((const unsigned*)((const char*)(gbase) + (voff)[_i]), (PG8_LAS unsigned*)(lds + (bufoff) + ldsw + _i * 8192), 16, 0, 0); } while (0)
; #define PG8_LDA(dst, b, h) do { _Pragma("unroll") for (int m = 0; m < 4; ++m) _Pragma("unroll") for (int k = 0; k < 2; ++k) dst[m][k] = *(const PG8_LAS bf16x8*)(lds + PG8_SA(b, h) + aoff + m * 2048 + k * 1024); } while (0)
; #define PG8_LDB(dst, b, h) do { _Pragma("unroll") for (int n = 0; n < 2; ++n) _Pragma("unroll") for (int k = 0; k < 2; ++k) dst[n][k] = *(const PG8_LAS bf16x8*)(lds + PG8_SB(b, h) + boff + n * 2048 + k * 1024); } while (0)
; #define PG8_MMA(ai, bj, At, Bt) do { __builtin_amdgcn_s_setprio(1); _Pragma("unroll") for (int m = 0; m < 4; ++m) _Pragma("unroll") for (int n = 0; n < 2; ++n) _Pragma("unroll") for (int k = 0; k < 2; ++k) \
;         acc[ai][bj][m][n] = __builtin_amdgcn_mfma_f32_16x16x32_bf16(Bt[n][k], At[m][k], acc[ai][bj][m][n], 0, 0, 0); __builtin_amdgcn_s_setprio(0); } while (0)
; #define PG8_WAIT_V(n) asm volatile("s_waitcnt vmcnt(" #n ")" ::: "memory")
; #define PG8_WAIT_L(n) asm volatile("s_waitcnt lgkmcnt(" #n ")" ::: "memory")
; #define PG8_BAR __builtin_amdgcn_s_barrier()
; #define PG8_SCHED __builtin_amdgcn_sched_barrier(0)
; template <class Epi, class Sched, bool ALIGN_EPI = false, bool SP2 = false>
; __device__ __forceinline__ void gemm_phase(PG8_LAS unsigned char* lds, const Gemm g, const Sched& S, const Epi& E, int wave_s) {
;     ...
;             PG8_LDB(B0, 0, 0); PG8_LDB(B1, 0, 1); PG8_SCHED; PG8_LDA(At, 0, 0); PG8_STAGE(PG8_SA(1, 1), a1 + hstep, voffA);
;             PG8_WAIT_V(8); PG8_WAIT_L(0); PG8_BAR; PG8_MMA(0, 0, At, B0); PG8_MMA(0, 1, At, B1); PG8_BAR; PG8_SCHED;
;             PG8_LDA(At, 0, 1); PG8_STAGE(PG8_SB(0, 0), b2, voffB); PG8_STAGE(PG8_SB(0, 1), b2 + hstep, voffB); PG8_STAGE(PG8_SA(0, 0), a2, voffA);
.LBB0_1138:
	ds_read_b128 v[146:149], v155
	ds_read_b128 v[158:161], v155 offset:1024
	ds_read_b128 v[162:165], v155 offset:2048
	ds_read_b128 v[166:169], v155 offset:3072
	ds_read_b128 v[170:173], v156
	ds_read_b128 v[174:177], v156 offset:1024
	ds_read_b128 v[178:181], v156 offset:2048
	ds_read_b128 v[182:185], v156 offset:3072
	s_add_u32 s44, s42, 0xfffc0080
	s_addc_u32 s45, s43, -1
	s_cmp_eq_u32 s75, 12
	s_cselect_b32 s47, s21, s45
	s_cselect_b32 s46, s27, s44
	s_cselect_b32 s45, s19, s74
	s_cselect_b32 s44, s41, s73
	v_lshl_add_u64 v[150:151], s[42:43], 0, v[138:139]
	s_add_i32 m0, s51, 0xc000
	ds_read_b128 v[186:189], v157
	ds_read_b128 v[190:193], v157 offset:1024
	ds_read_b128 v[194:197], v157 offset:2048
	ds_read_b128 v[198:201], v157 offset:3072
	ds_read_b128 v[202:205], v157 offset:4096
	ds_read_b128 v[206:209], v157 offset:5120
	ds_read_b128 v[214:217], v157 offset:6144
	ds_read_b128 v[218:221], v157 offset:7168
	global_load_lds_dwordx4 v[150:151], off
	s_add_i32 m0, s51, 0xe000
	v_lshl_add_u64 v[150:151], s[42:43], 0, v[140:141]
	global_load_lds_dwordx4 v[150:151], off
	s_waitcnt vmcnt(8)
	s_waitcnt lgkmcnt(0)
	s_barrier
	s_setprio 1
	s_waitcnt lgkmcnt(0)
	v_mfma_f32_16x16x32_bf16 v[124:127], v[146:149], v[186:189], v[124:127]
	v_mfma_f32_16x16x32_bf16 v[120:123], v[162:165], v[186:189], v[120:123]
	v_mfma_f32_16x16x32_bf16 v[108:111], v[146:149], v[194:197], v[108:111]
	v_mfma_f32_16x16x32_bf16 v[104:107], v[162:165], v[194:197], v[104:107]
	v_mfma_f32_16x16x32_bf16 v[92:95], v[146:149], v[202:205], v[92:95]
	v_mfma_f32_16x16x32_bf16 v[88:91], v[162:165], v[202:205], v[88:91]
	v_mfma_f32_16x16x32_bf16 v[76:79], v[146:149], v[214:217], v[76:79]
	v_mfma_f32_16x16x32_bf16 v[72:75], v[162:165], v[214:217], v[72:75]
	v_mfma_f32_16x16x32_bf16 v[124:127], v[158:161], v[190:193], v[124:127]
	v_mfma_f32_16x16x32_bf16 v[120:123], v[166:169], v[190:193], v[120:123]
	v_mfma_f32_16x16x32_bf16 v[108:111], v[158:161], v[198:201], v[108:111]
	v_mfma_f32_16x16x32_bf16 v[104:107], v[166:169], v[198:201], v[104:107]
	v_mfma_f32_16x16x32_bf16 v[92:95], v[158:161], v[206:209], v[92:95]
	v_mfma_f32_16x16x32_bf16 v[88:91], v[166:169], v[206:209], v[88:91]
	v_mfma_f32_16x16x32_bf16 v[76:79], v[158:161], v[218:221], v[76:79]
	v_mfma_f32_16x16x32_bf16 v[72:75], v[166:169], v[218:221], v[72:75]
	s_setprio 0
	s_setprio 1
	v_mfma_f32_16x16x32_bf16 v[116:119], v[170:173], v[186:189], v[116:119]
	v_mfma_f32_16x16x32_bf16 v[112:115], v[178:181], v[186:189], v[112:115]
	v_mfma_f32_16x16x32_bf16 v[100:103], v[170:173], v[194:197], v[100:103]
	v_mfma_f32_16x16x32_bf16 v[96:99], v[178:181], v[194:197], v[96:99]
	v_mfma_f32_16x16x32_bf16 v[84:87], v[170:173], v[202:205], v[84:87]
	v_mfma_f32_16x16x32_bf16 v[80:83], v[178:181], v[202:205], v[80:83]
	v_mfma_f32_16x16x32_bf16 v[68:71], v[170:173], v[214:217], v[68:71]
	v_mfma_f32_16x16x32_bf16 v[64:67], v[178:181], v[214:217], v[64:67]
	v_mfma_f32_16x16x32_bf16 v[116:119], v[174:177], v[190:193], v[116:119]
	v_mfma_f32_16x16x32_bf16 v[112:115], v[182:185], v[190:193], v[112:115]
	v_mfma_f32_16x16x32_bf16 v[100:103], v[174:177], v[198:201], v[100:103]
	v_mfma_f32_16x16x32_bf16 v[96:99], v[182:185], v[198:201], v[96:99]
	v_mfma_f32_16x16x32_bf16 v[84:87], v[174:177], v[206:209], v[84:87]
	v_mfma_f32_16x16x32_bf16 v[80:83], v[182:185], v[206:209], v[80:83]
	v_mfma_f32_16x16x32_bf16 v[68:71], v[174:177], v[218:221], v[68:71]
	v_mfma_f32_16x16x32_bf16 v[64:67], v[182:185], v[218:221], v[64:67]
	s_setprio 0
	s_barrier
	s_add_i32 s76, s66, s50
	v_lshl_add_u64 v[150:151], s[44:45], 0, v[130:131]
	s_mov_b32 m0, s76
	ds_read_b128 v[186:189], v157 offset:16384
	ds_read_b128 v[190:193], v157 offset:17408
	ds_read_b128 v[194:197], v157 offset:18432
	ds_read_b128 v[198:201], v157 offset:19456
	ds_read_b128 v[202:205], v157 offset:20480
	ds_read_b128 v[206:209], v157 offset:21504
	ds_read_b128 v[214:217], v157 offset:22528
	ds_read_b128 v[218:221], v157 offset:23552
	global_load_lds_dwordx4 v[150:151], off
	s_add_i32 m0, s76, 0x2000
	s_add_u32 s76, s44, 0x40000
	v_lshl_add_u64 v[210:211], s[44:45], 0, v[134:135]
	s_addc_u32 s77, s45, 0
	s_add_i32 s78, s67, s50
	global_load_lds_dwordx4 v[210:211], off
	v_lshl_add_u64 v[222:223], s[76:77], 0, v[130:131]
	s_mov_b32 m0, s78
	v_lshl_add_u64 v[224:225], s[46:47], 0, v[132:133]
	global_load_lds_dwordx4 v[222:223], off
	s_add_i32 m0, s78, 0x2000
	v_lshl_add_u64 v[222:223], s[76:77], 0, v[134:135]
	global_load_lds_dwordx4 v[222:223], off
	s_mov_b32 m0, s51
	v_lshl_add_u64 v[222:223], s[46:47], 0, v[128:129]
	global_load_lds_dwordx4 v[222:223], off
	s_mov_b32 m0, s56
	s_nop 0
	global_load_lds_dwordx4 v[224:225], off
	s_waitcnt vmcnt(8)
	s_waitcnt lgkmcnt(0)
	s_barrier
; #define PG8_STAGE(bufoff, gbase, voff) do { _Pragma("unroll") for (int _i = 0; _i < 2; ++_i) \
;         __builtin_amdgcn_global_load_lds((const unsigned*)((const char*)(gbase) + (voff)[_i]), (PG8_LAS unsigned*)(lds + (bufoff) + ldsw + _i * 8192), 16, 0, 0); } while (0)
; #define PG8_LDA(dst, b, h) do { _Pragma("unroll") for (int m = 0; m < 4; ++m) _Pragma("unroll") for (int k = 0; k < 2; ++k) dst[m][k] = *(const PG8_LAS bf16x8*)(lds + PG8_SA(b, h) + aoff + m * 2048 + k * 1024); } while (0)
; #define PG8_LDB(dst, b, h) do { _Pragma("unroll") for (int n = 0; n < 2; ++n) _Pragma("unroll") for (int k = 0; k < 2; ++k) dst[n][k] = *(const PG8_LAS bf16x8*)(lds + PG8_SB(b, h) + boff + n * 2048 + k * 1024); } while (0)
; #define PG8_MMA(ai, bj, At, Bt) do { __builtin_amdgcn_s_setprio(1); _Pragma("unroll") for (int m = 0; m < 4; ++m) _Pragma("unroll") for (int n = 0; n < 2; ++n) _Pragma("unroll") for (int k = 0; k < 2; ++k) \
;         acc[ai][bj][m][n] = __builtin_amdgcn_mfma_f32_16x16x32_bf16(Bt[n][k], At[m][k], acc[ai][bj][m][n], 0, 0, 0); __builtin_amdgcn_s_setprio(0); } while (0)
; #define PG8_WAIT_V(n) asm volatile("s_waitcnt vmcnt(" #n ")" ::: "memory")
; #define PG8_WAIT_L(n) asm volatile("s_waitcnt lgkmcnt(" #n ")" ::: "memory")
; #define PG8_BAR __builtin_amdgcn_s_barrier()
; #define PG8_SCHED __builtin_amdgcn_sched_barrier(0)
; template <class Epi, class Sched, bool ALIGN_EPI = false, bool SP2 = false>
; __device__ __forceinline__ void gemm_phase(PG8_LAS unsigned char* lds, const Gemm g, const Sched& S, const Epi& E, int wave_s) {
;     ...
;             PG8_WAIT_V(8); PG8_WAIT_L(0); PG8_BAR; PG8_MMA(1, 0, At, B0); PG8_MMA(1, 1, At, B1); PG8_BAR; PG8_SCHED;
;             PG8_LDB(B0, 1, 0); PG8_LDB(B1, 1, 1); PG8_SCHED; PG8_LDA(At, 1, 0); PG8_STAGE(PG8_SA(0, 1), a2 + hstep, voffA);
;             PG8_WAIT_V(8); PG8_WAIT_L(0); PG8_BAR; PG8_MMA(0, 0, At, B0); PG8_MMA(0, 1, At, B1); PG8_BAR; PG8_SCHED;
	s_setprio 1
	s_waitcnt lgkmcnt(0)
	v_mfma_f32_16x16x32_bf16 v[60:63], v[146:149], v[186:189], v[60:63]
	v_mfma_f32_16x16x32_bf16 v[56:59], v[162:165], v[186:189], v[56:59]
	v_mfma_f32_16x16x32_bf16 v[44:47], v[146:149], v[194:197], v[44:47]
	v_mfma_f32_16x16x32_bf16 v[40:43], v[162:165], v[194:197], v[40:43]
	v_mfma_f32_16x16x32_bf16 v[28:31], v[146:149], v[202:205], v[28:31]
	v_mfma_f32_16x16x32_bf16 v[24:27], v[162:165], v[202:205], v[24:27]
	v_mfma_f32_16x16x32_bf16 v[12:15], v[146:149], v[214:217], v[12:15]
	v_mfma_f32_16x16x32_bf16 v[8:11], v[162:165], v[214:217], v[8:11]
	v_mfma_f32_16x16x32_bf16 v[60:63], v[158:161], v[190:193], v[60:63]
	v_mfma_f32_16x16x32_bf16 v[56:59], v[166:169], v[190:193], v[56:59]
	v_mfma_f32_16x16x32_bf16 v[44:47], v[158:161], v[198:201], v[44:47]
	v_mfma_f32_16x16x32_bf16 v[40:43], v[166:169], v[198:201], v[40:43]
	v_mfma_f32_16x16x32_bf16 v[28:31], v[158:161], v[206:209], v[28:31]
	v_mfma_f32_16x16x32_bf16 v[24:27], v[166:169], v[206:209], v[24:27]
	v_mfma_f32_16x16x32_bf16 v[12:15], v[158:161], v[218:221], v[12:15]
	v_mfma_f32_16x16x32_bf16 v[8:11], v[166:169], v[218:221], v[8:11]
	s_setprio 0
	s_setprio 1
	v_mfma_f32_16x16x32_bf16 v[52:55], v[170:173], v[186:189], v[52:55]
	v_mfma_f32_16x16x32_bf16 v[48:51], v[178:181], v[186:189], v[48:51]
	v_mfma_f32_16x16x32_bf16 v[36:39], v[170:173], v[194:197], v[36:39]
	v_mfma_f32_16x16x32_bf16 v[32:35], v[178:181], v[194:197], v[32:35]
	v_mfma_f32_16x16x32_bf16 v[20:23], v[170:173], v[202:205], v[20:23]
	v_mfma_f32_16x16x32_bf16 v[16:19], v[178:181], v[202:205], v[16:19]
	v_mfma_f32_16x16x32_bf16 v[4:7], v[170:173], v[214:217], v[4:7]
	v_mfma_f32_16x16x32_bf16 v[0:3], v[178:181], v[214:217], v[0:3]
	v_mfma_f32_16x16x32_bf16 v[52:55], v[174:177], v[190:193], v[52:55]
	v_mfma_f32_16x16x32_bf16 v[48:51], v[182:185], v[190:193], v[48:51]
	v_mfma_f32_16x16x32_bf16 v[36:39], v[174:177], v[198:201], v[36:39]
	v_mfma_f32_16x16x32_bf16 v[32:35], v[182:185], v[198:201], v[32:35]
	v_mfma_f32_16x16x32_bf16 v[20:23], v[174:177], v[206:209], v[20:23]
	v_mfma_f32_16x16x32_bf16 v[16:19], v[182:185], v[206:209], v[16:19]
	v_mfma_f32_16x16x32_bf16 v[4:7], v[174:177], v[218:221], v[4:7]
	v_mfma_f32_16x16x32_bf16 v[0:3], v[182:185], v[218:221], v[0:3]
	s_setprio 0
	s_barrier
	s_add_i32 s76, 0, 0x18000
	v_add_u32_e32 v136, s76, v153
	s_add_i32 s77, 0, 0x1c000
	ds_read_b128 v[146:149], v136
	ds_read_b128 v[158:161], v136 offset:1024
	ds_read_b128 v[162:165], v136 offset:2048
	ds_read_b128 v[166:169], v136 offset:3072
	v_add_u32_e32 v136, s77, v153
	ds_read_b128 v[170:173], v136
	ds_read_b128 v[174:177], v136 offset:1024
	ds_read_b128 v[178:181], v136 offset:2048
	ds_read_b128 v[182:185], v136 offset:3072
	s_add_u32 s46, s46, 0x40000
	s_addc_u32 s47, s47, 0
	s_mov_b32 m0, s57
	v_lshl_add_u64 v[226:227], s[46:47], 0, v[128:129]
	ds_read_b128 v[186:189], v157 offset:32768
	ds_read_b128 v[190:193], v157 offset:33792
	ds_read_b128 v[194:197], v157 offset:34816
	ds_read_b128 v[198:201], v157 offset:35840
	ds_read_b128 v[202:205], v157 offset:36864
	ds_read_b128 v[206:209], v157 offset:37888
	ds_read_b128 v[214:217], v157 offset:38912
	ds_read_b128 v[218:221], v157 offset:39936
	global_load_lds_dwordx4 v[226:227], off
	s_mov_b32 m0, s58
	v_lshl_add_u64 v[226:227], s[46:47], 0, v[132:133]
	global_load_lds_dwordx4 v[226:227], off
	s_waitcnt vmcnt(8)
	s_waitcnt lgkmcnt(0)
	s_barrier
	s_setprio 1
	s_waitcnt lgkmcnt(0)
	v_mfma_f32_16x16x32_bf16 v[124:127], v[146:149], v[186:189], v[124:127]
	v_mfma_f32_16x16x32_bf16 v[120:123], v[162:165], v[186:189], v[120:123]
	v_mfma_f32_16x16x32_bf16 v[108:111], v[146:149], v[194:197], v[108:111]
	v_mfma_f32_16x16x32_bf16 v[104:107], v[162:165], v[194:197], v[104:107]
	v_mfma_f32_16x16x32_bf16 v[92:95], v[146:149], v[202:205], v[92:95]
	v_mfma_f32_16x16x32_bf16 v[88:91], v[162:165], v[202:205], v[88:91]
	v_mfma_f32_16x16x32_bf16 v[76:79], v[146:149], v[214:217], v[76:79]
	v_mfma_f32_16x16x32_bf16 v[72:75], v[162:165], v[214:217], v[72:75]
	v_mfma_f32_16x16x32_bf16 v[124:127], v[158:161], v[190:193], v[124:127]
	v_mfma_f32_16x16x32_bf16 v[120:123], v[166:169], v[190:193], v[120:123]
	v_mfma_f32_16x16x32_bf16 v[108:111], v[158:161], v[198:201], v[108:111]
	v_mfma_f32_16x16x32_bf16 v[104:107], v[166:169], v[198:201], v[104:107]
	v_mfma_f32_16x16x32_bf16 v[92:95], v[158:161], v[206:209], v[92:95]
	v_mfma_f32_16x16x32_bf16 v[88:91], v[166:169], v[206:209], v[88:91]
	v_mfma_f32_16x16x32_bf16 v[76:79], v[158:161], v[218:221], v[76:79]
	v_mfma_f32_16x16x32_bf16 v[72:75], v[166:169], v[218:221], v[72:75]
	s_setprio 0
	s_setprio 1
	v_mfma_f32_16x16x32_bf16 v[116:119], v[170:173], v[186:189], v[116:119]
	v_mfma_f32_16x16x32_bf16 v[112:115], v[178:181], v[186:189], v[112:115]
	v_mfma_f32_16x16x32_bf16 v[100:103], v[170:173], v[194:197], v[100:103]
	v_mfma_f32_16x16x32_bf16 v[96:99], v[178:181], v[194:197], v[96:99]
	v_mfma_f32_16x16x32_bf16 v[84:87], v[170:173], v[202:205], v[84:87]
	v_mfma_f32_16x16x32_bf16 v[80:83], v[178:181], v[202:205], v[80:83]
	v_mfma_f32_16x16x32_bf16 v[68:71], v[170:173], v[214:217], v[68:71]
	v_mfma_f32_16x16x32_bf16 v[64:67], v[178:181], v[214:217], v[64:67]
	v_mfma_f32_16x16x32_bf16 v[116:119], v[174:177], v[190:193], v[116:119]
	v_mfma_f32_16x16x32_bf16 v[112:115], v[182:185], v[190:193], v[112:115]
	v_mfma_f32_16x16x32_bf16 v[100:103], v[174:177], v[198:201], v[100:103]
	v_mfma_f32_16x16x32_bf16 v[96:99], v[182:185], v[198:201], v[96:99]
	v_mfma_f32_16x16x32_bf16 v[84:87], v[174:177], v[206:209], v[84:87]
	v_mfma_f32_16x16x32_bf16 v[80:83], v[182:185], v[206:209], v[80:83]
	v_mfma_f32_16x16x32_bf16 v[68:71], v[174:177], v[218:221], v[68:71]
	v_mfma_f32_16x16x32_bf16 v[64:67], v[182:185], v[218:221], v[64:67]
	s_setprio 0
	s_barrier
; #define PG8_STAGE(bufoff, gbase, voff) do { _Pragma("unroll") for (int _i = 0; _i < 2; ++_i) \
;         __builtin_amdgcn_global_load_lds((const unsigned*)((const char*)(gbase) + (voff)[_i]), (PG8_LAS unsigned*)(lds + (bufoff) + ldsw + _i * 8192), 16, 0, 0); } while (0)
; #define PG8_LDA(dst, b, h) do { _Pragma("unroll") for (int m = 0; m < 4; ++m) _Pragma("unroll") for (int k = 0; k < 2; ++k) dst[m][k] = *(const PG8_LAS bf16x8*)(lds + PG8_SA(b, h) + aoff + m * 2048 + k * 1024); } while (0)
; #define PG8_MMA(ai, bj, At, Bt) do { __builtin_amdgcn_s_setprio(1); _Pragma("unroll") for (int m = 0; m < 4; ++m) _Pragma("unroll") for (int n = 0; n < 2; ++n) _Pragma("unroll") for (int k = 0; k < 2; ++k) \
;         acc[ai][bj][m][n] = __builtin_amdgcn_mfma_f32_16x16x32_bf16(Bt[n][k], At[m][k], acc[ai][bj][m][n], 0, 0, 0); __builtin_amdgcn_s_setprio(0); } while (0)
; #define PG8_WAIT_V(n) asm volatile("s_waitcnt vmcnt(" #n ")" ::: "memory")
; #define PG8_WAIT_L(n) asm volatile("s_waitcnt lgkmcnt(" #n ")" ::: "memory")
; #define PG8_BAR __builtin_amdgcn_s_barrier()
; #define PG8_SCHED __builtin_amdgcn_sched_barrier(0)
; template <class Epi, class Sched, bool ALIGN_EPI = false, bool SP2 = false>
; __device__ __forceinline__ void gemm_phase(PG8_LAS unsigned char* lds, const Gemm g, const Sched& S, const Epi& E, int wave_s) {
;     ...
;             PG8_LDA(At, 1, 1); PG8_STAGE(PG8_SB(1, 0), b3, voffB); PG8_STAGE(PG8_SB(1, 1), b3 + hstep, voffB); PG8_STAGE(PG8_SA(1, 0), a3, voffA);
;             PG8_WAIT_V(8); PG8_WAIT_L(0); PG8_BAR; PG8_MMA(1, 0, At, B0); PG8_MMA(1, 1, At, B1); PG8_BAR; PG8_SCHED;
	s_add_i32 s46, s76, s50
	v_lshl_add_u64 v[150:151], v[150:151], 0, s[12:13]
	s_mov_b32 m0, s46
	ds_read_b128 v[186:189], v157 offset:49152
	ds_read_b128 v[190:193], v157 offset:50176
	ds_read_b128 v[194:197], v157 offset:51200
	ds_read_b128 v[198:201], v157 offset:52224
	ds_read_b128 v[202:205], v157 offset:53248
	ds_read_b128 v[206:209], v157 offset:54272
	ds_read_b128 v[214:217], v157 offset:55296
	ds_read_b128 v[218:221], v157 offset:56320
	global_load_lds_dwordx4 v[150:151], off
	s_add_i32 m0, s46, 0x2000
	s_add_u32 s44, s44, 0x40080
	v_lshl_add_u64 v[150:151], v[210:211], 0, s[12:13]
	s_addc_u32 s45, s45, 0
	s_add_i32 s46, s77, s50
	global_load_lds_dwordx4 v[150:151], off
	s_mov_b32 m0, s46
	v_lshl_add_u64 v[150:151], s[44:45], 0, v[130:131]
	global_load_lds_dwordx4 v[150:151], off
	s_add_i32 m0, s46, 0x2000
	v_lshl_add_u64 v[150:151], s[44:45], 0, v[134:135]
	global_load_lds_dwordx4 v[150:151], off
	s_mov_b32 m0, s60
	v_lshl_add_u64 v[150:151], v[222:223], 0, s[12:13]
	global_load_lds_dwordx4 v[150:151], off
	s_mov_b32 m0, s61
	v_lshl_add_u64 v[150:151], v[224:225], 0, s[12:13]
	global_load_lds_dwordx4 v[150:151], off
	s_waitcnt vmcnt(8)
	s_waitcnt lgkmcnt(0)
	s_barrier
	s_setprio 1
	s_waitcnt lgkmcnt(0)
	v_mfma_f32_16x16x32_bf16 v[60:63], v[146:149], v[186:189], v[60:63]
	v_mfma_f32_16x16x32_bf16 v[56:59], v[162:165], v[186:189], v[56:59]
	v_mfma_f32_16x16x32_bf16 v[44:47], v[146:149], v[194:197], v[44:47]
	v_mfma_f32_16x16x32_bf16 v[40:43], v[162:165], v[194:197], v[40:43]
	v_mfma_f32_16x16x32_bf16 v[28:31], v[146:149], v[202:205], v[28:31]
	v_mfma_f32_16x16x32_bf16 v[24:27], v[162:165], v[202:205], v[24:27]
	v_mfma_f32_16x16x32_bf16 v[12:15], v[146:149], v[214:217], v[12:15]
	v_mfma_f32_16x16x32_bf16 v[8:11], v[162:165], v[214:217], v[8:11]
	v_mfma_f32_16x16x32_bf16 v[60:63], v[158:161], v[190:193], v[60:63]
	v_mfma_f32_16x16x32_bf16 v[56:59], v[166:169], v[190:193], v[56:59]
	v_mfma_f32_16x16x32_bf16 v[44:47], v[158:161], v[198:201], v[44:47]
	v_mfma_f32_16x16x32_bf16 v[40:43], v[166:169], v[198:201], v[40:43]
	v_mfma_f32_16x16x32_bf16 v[28:31], v[158:161], v[206:209], v[28:31]
	v_mfma_f32_16x16x32_bf16 v[24:27], v[166:169], v[206:209], v[24:27]
	v_mfma_f32_16x16x32_bf16 v[12:15], v[158:161], v[218:221], v[12:15]
	v_mfma_f32_16x16x32_bf16 v[8:11], v[166:169], v[218:221], v[8:11]
	s_setprio 0
	s_setprio 1
	v_mfma_f32_16x16x32_bf16 v[52:55], v[170:173], v[186:189], v[52:55]
	v_mfma_f32_16x16x32_bf16 v[48:51], v[178:181], v[186:189], v[48:51]
	v_mfma_f32_16x16x32_bf16 v[36:39], v[170:173], v[194:197], v[36:39]
	v_mfma_f32_16x16x32_bf16 v[32:35], v[178:181], v[194:197], v[32:35]
	v_mfma_f32_16x16x32_bf16 v[20:23], v[170:173], v[202:205], v[20:23]
	v_mfma_f32_16x16x32_bf16 v[16:19], v[178:181], v[202:205], v[16:19]
	v_mfma_f32_16x16x32_bf16 v[4:7], v[170:173], v[214:217], v[4:7]
	v_mfma_f32_16x16x32_bf16 v[0:3], v[178:181], v[214:217], v[0:3]
	v_mfma_f32_16x16x32_bf16 v[52:55], v[174:177], v[190:193], v[52:55]
	v_mfma_f32_16x16x32_bf16 v[48:51], v[182:185], v[190:193], v[48:51]
	v_mfma_f32_16x16x32_bf16 v[36:39], v[174:177], v[198:201], v[36:39]
	v_mfma_f32_16x16x32_bf16 v[32:35], v[182:185], v[198:201], v[32:35]
	v_mfma_f32_16x16x32_bf16 v[20:23], v[174:177], v[206:209], v[20:23]
	v_mfma_f32_16x16x32_bf16 v[16:19], v[182:185], v[206:209], v[16:19]
	v_mfma_f32_16x16x32_bf16 v[4:7], v[174:177], v[218:221], v[4:7]
	v_mfma_f32_16x16x32_bf16 v[0:3], v[182:185], v[218:221], v[0:3]
	s_setprio 0
	s_barrier
	s_add_i32 s75, s75, 2
	s_add_u32 s42, s42, 0x100
	s_addc_u32 s43, s43, 0
	s_add_u32 s73, s73, 0x100
	s_addc_u32 s74, s74, 0
	s_cmp_gt_u32 s75, 13
	s_cbranch_scc0 .LBB0_1138
	s_and_b64 vcc, exec, s[16:17]
	s_cbranch_vccz .LBB0_1141
	s_barrier

; #define PG8_STAGE(bufoff, gbase, voff) do { _Pragma("unroll") for (int _i = 0; _i < 2; ++_i) \
;         __builtin_amdgcn_global_load_lds((const unsigned*)((const char*)(gbase) + (voff)[_i]), (PG8_LAS unsigned*)(lds + (bufoff) + ldsw + _i * 8192), 16, 0, 0); } while (0)
; #define PG8_LDA(dst, b, h) do { _Pragma("unroll") for (int m = 0; m < 4; ++m) _Pragma("unroll") for (int k = 0; k < 2; ++k) dst[m][k] = *(const PG8_LAS bf16x8*)(lds + PG8_SA(b, h) + aoff + m * 2048 + k * 1024); } while (0)
; #define PG8_LDB(dst, b, h) do { _Pragma("unroll") for (int n = 0; n < 2; ++n) _Pragma("unroll") for (int k = 0; k < 2; ++k) dst[n][k] = *(const PG8_LAS bf16x8*)(lds + PG8_SB(b, h) + boff + n * 2048 + k * 1024); } while (0)
; #define PG8_MMA(ai, bj, At, Bt) do { __builtin_amdgcn_s_setprio(1); _Pragma("unroll") for (int m = 0; m < 4; ++m) _Pragma("unroll") for (int n = 0; n < 2; ++n) _Pragma("unroll") for (int k = 0; k < 2; ++k) \
;         acc[ai][bj][m][n] = __builtin_amdgcn_mfma_f32_16x16x32_bf16(Bt[n][k], At[m][k], acc[ai][bj][m][n], 0, 0, 0); __builtin_amdgcn_s_setprio(0); } while (0)
; #define PG8_WAIT_V(n) asm volatile("s_waitcnt vmcnt(" #n ")" ::: "memory")
; #define PG8_WAIT_L(n) asm volatile("s_waitcnt lgkmcnt(" #n ")" ::: "memory")
; #define PG8_BAR __builtin_amdgcn_s_barrier()
; #define PG8_SCHED __builtin_amdgcn_sched_barrier(0)
; template <class Epi, class Sched, bool ALIGN_EPI = false, bool SP2 = false>
; __device__ __forceinline__ void gemm_phase(PG8_LAS unsigned char* lds, const Gemm g, const Sched& S, const Epi& E, int wave_s) {
;     ...
;             PG8_LDB(B0, 0, 0); PG8_LDB(B1, 0, 1); PG8_SCHED; PG8_LDA(At, 0, 0); PG8_STAGE(PG8_SA(1, 1), a1 + hstep, voffA);
;             PG8_WAIT_V(8); PG8_WAIT_L(0); PG8_BAR; PG8_MMA(0, 0, At, B0); PG8_MMA(0, 1, At, B1); PG8_BAR; PG8_SCHED;
;             PG8_LDA(At, 0, 1); PG8_STAGE(PG8_SB(0, 0), b2, voffB); PG8_STAGE(PG8_SB(0, 1), b2 + hstep, voffB); PG8_STAGE(PG8_SA(0, 0), a2, voffA);
.LBB0_1257:
	ds_read_b128 v[154:157], v149
	ds_read_b128 v[158:161], v149 offset:1024
	ds_read_b128 v[162:165], v149 offset:2048
	ds_read_b128 v[166:169], v149 offset:3072
	ds_read_b128 v[170:173], v150
	ds_read_b128 v[174:177], v150 offset:1024
	ds_read_b128 v[178:181], v150 offset:2048
	ds_read_b128 v[182:185], v150 offset:3072
	s_add_u32 s38, s36, 0xfffc0080
	s_addc_u32 s39, s37, -1
	s_cmp_eq_u32 s68, 12
	s_cselect_b32 s41, s23, s39
	s_cselect_b32 s40, s64, s38
	s_cselect_b32 s39, s21, s67
	s_cselect_b32 s38, s65, s66
	v_lshl_add_u64 v[144:145], s[36:37], 0, v[136:137]
	s_add_i32 m0, s48, 0xc000
	ds_read_b128 v[186:189], v151
	ds_read_b128 v[190:193], v151 offset:1024
	ds_read_b128 v[194:197], v151 offset:2048
	ds_read_b128 v[198:201], v151 offset:3072
	ds_read_b128 v[202:205], v151 offset:4096
	ds_read_b128 v[206:209], v151 offset:5120
	ds_read_b128 v[214:217], v151 offset:6144
	ds_read_b128 v[218:221], v151 offset:7168
	global_load_lds_dwordx4 v[144:145], off
	s_add_i32 m0, s48, 0xe000
	v_lshl_add_u64 v[144:145], s[36:37], 0, v[138:139]
	global_load_lds_dwordx4 v[144:145], off
	s_waitcnt vmcnt(8)
	s_waitcnt lgkmcnt(0)
	s_barrier
	s_setprio 1
	s_waitcnt lgkmcnt(0)
	v_mfma_f32_16x16x32_bf16 v[120:123], v[154:157], v[186:189], v[120:123]
	v_mfma_f32_16x16x32_bf16 v[112:115], v[162:165], v[186:189], v[112:115]
	v_mfma_f32_16x16x32_bf16 v[104:107], v[154:157], v[194:197], v[104:107]
	v_mfma_f32_16x16x32_bf16 v[100:103], v[162:165], v[194:197], v[100:103]
	v_mfma_f32_16x16x32_bf16 v[88:91], v[154:157], v[202:205], v[88:91]
	v_mfma_f32_16x16x32_bf16 v[84:87], v[162:165], v[202:205], v[84:87]
	v_mfma_f32_16x16x32_bf16 v[76:79], v[154:157], v[214:217], v[76:79]
	v_mfma_f32_16x16x32_bf16 v[68:71], v[162:165], v[214:217], v[68:71]
	v_mfma_f32_16x16x32_bf16 v[120:123], v[158:161], v[190:193], v[120:123]
	v_mfma_f32_16x16x32_bf16 v[112:115], v[166:169], v[190:193], v[112:115]
	v_mfma_f32_16x16x32_bf16 v[104:107], v[158:161], v[198:201], v[104:107]
	v_mfma_f32_16x16x32_bf16 v[100:103], v[166:169], v[198:201], v[100:103]
	v_mfma_f32_16x16x32_bf16 v[88:91], v[158:161], v[206:209], v[88:91]
	v_mfma_f32_16x16x32_bf16 v[84:87], v[166:169], v[206:209], v[84:87]
	v_mfma_f32_16x16x32_bf16 v[76:79], v[158:161], v[218:221], v[76:79]
	v_mfma_f32_16x16x32_bf16 v[68:71], v[166:169], v[218:221], v[68:71]
	s_setprio 0
	s_setprio 1
	v_mfma_f32_16x16x32_bf16 v[124:127], v[170:173], v[186:189], v[124:127]
	v_mfma_f32_16x16x32_bf16 v[116:119], v[178:181], v[186:189], v[116:119]
	v_mfma_f32_16x16x32_bf16 v[108:111], v[170:173], v[194:197], v[108:111]
	v_mfma_f32_16x16x32_bf16 v[96:99], v[178:181], v[194:197], v[96:99]
	v_mfma_f32_16x16x32_bf16 v[92:95], v[170:173], v[202:205], v[92:95]
	v_mfma_f32_16x16x32_bf16 v[80:83], v[178:181], v[202:205], v[80:83]
	v_mfma_f32_16x16x32_bf16 v[72:75], v[170:173], v[214:217], v[72:75]
	v_mfma_f32_16x16x32_bf16 v[64:67], v[178:181], v[214:217], v[64:67]
	v_mfma_f32_16x16x32_bf16 v[124:127], v[174:177], v[190:193], v[124:127]
	v_mfma_f32_16x16x32_bf16 v[116:119], v[182:185], v[190:193], v[116:119]
	v_mfma_f32_16x16x32_bf16 v[108:111], v[174:177], v[198:201], v[108:111]
	v_mfma_f32_16x16x32_bf16 v[96:99], v[182:185], v[198:201], v[96:99]
	v_mfma_f32_16x16x32_bf16 v[92:95], v[174:177], v[206:209], v[92:95]
	v_mfma_f32_16x16x32_bf16 v[80:83], v[182:185], v[206:209], v[80:83]
	v_mfma_f32_16x16x32_bf16 v[72:75], v[174:177], v[218:221], v[72:75]
	v_mfma_f32_16x16x32_bf16 v[64:67], v[182:185], v[218:221], v[64:67]
	s_setprio 0
	s_barrier
	s_add_i32 s69, s60, s45
	v_lshl_add_u64 v[144:145], s[38:39], 0, v[132:133]
	s_mov_b32 m0, s69
	ds_read_b128 v[186:189], v151 offset:16384
	ds_read_b128 v[190:193], v151 offset:17408
	ds_read_b128 v[194:197], v151 offset:18432
	ds_read_b128 v[198:201], v151 offset:19456
	ds_read_b128 v[202:205], v151 offset:20480
	ds_read_b128 v[206:209], v151 offset:21504
	ds_read_b128 v[214:217], v151 offset:22528
	ds_read_b128 v[218:221], v151 offset:23552
	global_load_lds_dwordx4 v[144:145], off
	s_add_i32 m0, s69, 0x2000
	s_add_u32 s70, s38, 0x40000
	v_lshl_add_u64 v[210:211], s[38:39], 0, v[128:129]
	s_addc_u32 s71, s39, 0
	s_add_i32 s69, s61, s45
	global_load_lds_dwordx4 v[210:211], off
	v_lshl_add_u64 v[222:223], s[70:71], 0, v[132:133]
	s_mov_b32 m0, s69
	v_lshl_add_u64 v[224:225], s[40:41], 0, v[130:131]
	global_load_lds_dwordx4 v[222:223], off
	s_add_i32 m0, s69, 0x2000
	v_lshl_add_u64 v[222:223], s[70:71], 0, v[128:129]
	global_load_lds_dwordx4 v[222:223], off
	s_mov_b32 m0, s48
	v_lshl_add_u64 v[222:223], s[40:41], 0, v[134:135]
	global_load_lds_dwordx4 v[222:223], off
	s_mov_b32 m0, s49
	s_nop 0
	global_load_lds_dwordx4 v[224:225], off
	s_waitcnt vmcnt(8)
	s_waitcnt lgkmcnt(0)
	s_barrier
; #define PG8_STAGE(bufoff, gbase, voff) do { _Pragma("unroll") for (int _i = 0; _i < 2; ++_i) \
;         __builtin_amdgcn_global_load_lds((const unsigned*)((const char*)(gbase) + (voff)[_i]), (PG8_LAS unsigned*)(lds + (bufoff) + ldsw + _i * 8192), 16, 0, 0); } while (0)
; #define PG8_LDA(dst, b, h) do { _Pragma("unroll") for (int m = 0; m < 4; ++m) _Pragma("unroll") for (int k = 0; k < 2; ++k) dst[m][k] = *(const PG8_LAS bf16x8*)(lds + PG8_SA(b, h) + aoff + m * 2048 + k * 1024); } while (0)
; #define PG8_LDB(dst, b, h) do { _Pragma("unroll") for (int n = 0; n < 2; ++n) _Pragma("unroll") for (int k = 0; k < 2; ++k) dst[n][k] = *(const PG8_LAS bf16x8*)(lds + PG8_SB(b, h) + boff + n * 2048 + k * 1024); } while (0)
; #define PG8_MMA(ai, bj, At, Bt) do { __builtin_amdgcn_s_setprio(1); _Pragma("unroll") for (int m = 0; m < 4; ++m) _Pragma("unroll") for (int n = 0; n < 2; ++n) _Pragma("unroll") for (int k = 0; k < 2; ++k) \
;         acc[ai][bj][m][n] = __builtin_amdgcn_mfma_f32_16x16x32_bf16(Bt[n][k], At[m][k], acc[ai][bj][m][n], 0, 0, 0); __builtin_amdgcn_s_setprio(0); } while (0)
; #define PG8_WAIT_V(n) asm volatile("s_waitcnt vmcnt(" #n ")" ::: "memory")
; #define PG8_WAIT_L(n) asm volatile("s_waitcnt lgkmcnt(" #n ")" ::: "memory")
; #define PG8_BAR __builtin_amdgcn_s_barrier()
; #define PG8_SCHED __builtin_amdgcn_sched_barrier(0)
; template <class Epi, class Sched, bool ALIGN_EPI = false, bool SP2 = false>
; __device__ __forceinline__ void gemm_phase(PG8_LAS unsigned char* lds, const Gemm g, const Sched& S, const Epi& E, int wave_s) {
;     ...
;             PG8_WAIT_V(8); PG8_WAIT_L(0); PG8_BAR; PG8_MMA(1, 0, At, B0); PG8_MMA(1, 1, At, B1); PG8_BAR; PG8_SCHED;
;             PG8_LDB(B0, 1, 0); PG8_LDB(B1, 1, 1); PG8_SCHED; PG8_LDA(At, 1, 0); PG8_STAGE(PG8_SA(0, 1), a2 + hstep, voffA);
;             PG8_WAIT_V(8); PG8_WAIT_L(0); PG8_BAR; PG8_MMA(0, 0, At, B0); PG8_MMA(0, 1, At, B1); PG8_BAR; PG8_SCHED;
	s_setprio 1
	s_waitcnt lgkmcnt(0)
	v_mfma_f32_16x16x32_bf16 v[60:63], v[154:157], v[186:189], v[60:63]
	v_mfma_f32_16x16x32_bf16 v[56:59], v[162:165], v[186:189], v[56:59]
	v_mfma_f32_16x16x32_bf16 v[44:47], v[154:157], v[194:197], v[44:47]
	v_mfma_f32_16x16x32_bf16 v[40:43], v[162:165], v[194:197], v[40:43]
	v_mfma_f32_16x16x32_bf16 v[28:31], v[154:157], v[202:205], v[28:31]
	v_mfma_f32_16x16x32_bf16 v[24:27], v[162:165], v[202:205], v[24:27]
	v_mfma_f32_16x16x32_bf16 v[12:15], v[154:157], v[214:217], v[12:15]
	v_mfma_f32_16x16x32_bf16 v[8:11], v[162:165], v[214:217], v[8:11]
	v_mfma_f32_16x16x32_bf16 v[60:63], v[158:161], v[190:193], v[60:63]
	v_mfma_f32_16x16x32_bf16 v[56:59], v[166:169], v[190:193], v[56:59]
	v_mfma_f32_16x16x32_bf16 v[44:47], v[158:161], v[198:201], v[44:47]
	v_mfma_f32_16x16x32_bf16 v[40:43], v[166:169], v[198:201], v[40:43]
	v_mfma_f32_16x16x32_bf16 v[28:31], v[158:161], v[206:209], v[28:31]
	v_mfma_f32_16x16x32_bf16 v[24:27], v[166:169], v[206:209], v[24:27]
	v_mfma_f32_16x16x32_bf16 v[12:15], v[158:161], v[218:221], v[12:15]
	v_mfma_f32_16x16x32_bf16 v[8:11], v[166:169], v[218:221], v[8:11]
	s_setprio 0
	s_setprio 1
	v_mfma_f32_16x16x32_bf16 v[52:55], v[170:173], v[186:189], v[52:55]
	v_mfma_f32_16x16x32_bf16 v[48:51], v[178:181], v[186:189], v[48:51]
	v_mfma_f32_16x16x32_bf16 v[36:39], v[170:173], v[194:197], v[36:39]
	v_mfma_f32_16x16x32_bf16 v[32:35], v[178:181], v[194:197], v[32:35]
	v_mfma_f32_16x16x32_bf16 v[20:23], v[170:173], v[202:205], v[20:23]
	v_mfma_f32_16x16x32_bf16 v[16:19], v[178:181], v[202:205], v[16:19]
	v_mfma_f32_16x16x32_bf16 v[4:7], v[170:173], v[214:217], v[4:7]
	v_mfma_f32_16x16x32_bf16 v[0:3], v[178:181], v[214:217], v[0:3]
	v_mfma_f32_16x16x32_bf16 v[52:55], v[174:177], v[190:193], v[52:55]
	v_mfma_f32_16x16x32_bf16 v[48:51], v[182:185], v[190:193], v[48:51]
	v_mfma_f32_16x16x32_bf16 v[36:39], v[174:177], v[198:201], v[36:39]
	v_mfma_f32_16x16x32_bf16 v[32:35], v[182:185], v[198:201], v[32:35]
	v_mfma_f32_16x16x32_bf16 v[20:23], v[174:177], v[206:209], v[20:23]
	v_mfma_f32_16x16x32_bf16 v[16:19], v[182:185], v[206:209], v[16:19]
	v_mfma_f32_16x16x32_bf16 v[4:7], v[174:177], v[218:221], v[4:7]
	v_mfma_f32_16x16x32_bf16 v[0:3], v[182:185], v[218:221], v[0:3]
	s_setprio 0
	s_barrier
	s_add_i32 s69, 0, 0x18000
	s_add_i32 s70, 0, 0x1c000
	v_add_u32_e32 v166, s69, v147
	v_add_u32_e32 v182, s70, v147
	ds_read_b128 v[154:157], v166
	ds_read_b128 v[158:161], v166 offset:1024
	ds_read_b128 v[162:165], v166 offset:2048
	ds_read_b128 v[166:169], v166 offset:3072
	ds_read_b128 v[170:173], v182
	ds_read_b128 v[174:177], v182 offset:1024
	ds_read_b128 v[178:181], v182 offset:2048
	ds_read_b128 v[182:185], v182 offset:3072
	s_add_u32 s40, s40, 0x40000
	s_addc_u32 s41, s41, 0
	s_mov_b32 m0, s50
	v_lshl_add_u64 v[226:227], s[40:41], 0, v[134:135]
	ds_read_b128 v[186:189], v151 offset:32768
	ds_read_b128 v[190:193], v151 offset:33792
	ds_read_b128 v[194:197], v151 offset:34816
	ds_read_b128 v[198:201], v151 offset:35840
	ds_read_b128 v[202:205], v151 offset:36864
	ds_read_b128 v[206:209], v151 offset:37888
	ds_read_b128 v[214:217], v151 offset:38912
	ds_read_b128 v[218:221], v151 offset:39936
	global_load_lds_dwordx4 v[226:227], off
	s_mov_b32 m0, s51
	v_lshl_add_u64 v[226:227], s[40:41], 0, v[130:131]
	global_load_lds_dwordx4 v[226:227], off
	s_waitcnt vmcnt(8)
	s_waitcnt lgkmcnt(0)
	s_barrier
	s_setprio 1
	s_waitcnt lgkmcnt(0)
	v_mfma_f32_16x16x32_bf16 v[120:123], v[154:157], v[186:189], v[120:123]
	v_mfma_f32_16x16x32_bf16 v[112:115], v[162:165], v[186:189], v[112:115]
	v_mfma_f32_16x16x32_bf16 v[104:107], v[154:157], v[194:197], v[104:107]
	v_mfma_f32_16x16x32_bf16 v[100:103], v[162:165], v[194:197], v[100:103]
	v_mfma_f32_16x16x32_bf16 v[88:91], v[154:157], v[202:205], v[88:91]
	v_mfma_f32_16x16x32_bf16 v[84:87], v[162:165], v[202:205], v[84:87]
	v_mfma_f32_16x16x32_bf16 v[76:79], v[154:157], v[214:217], v[76:79]
	v_mfma_f32_16x16x32_bf16 v[68:71], v[162:165], v[214:217], v[68:71]
	v_mfma_f32_16x16x32_bf16 v[120:123], v[158:161], v[190:193], v[120:123]
	v_mfma_f32_16x16x32_bf16 v[112:115], v[166:169], v[190:193], v[112:115]
	v_mfma_f32_16x16x32_bf16 v[104:107], v[158:161], v[198:201], v[104:107]
	v_mfma_f32_16x16x32_bf16 v[100:103], v[166:169], v[198:201], v[100:103]
	v_mfma_f32_16x16x32_bf16 v[88:91], v[158:161], v[206:209], v[88:91]
	v_mfma_f32_16x16x32_bf16 v[84:87], v[166:169], v[206:209], v[84:87]
	v_mfma_f32_16x16x32_bf16 v[76:79], v[158:161], v[218:221], v[76:79]
	v_mfma_f32_16x16x32_bf16 v[68:71], v[166:169], v[218:221], v[68:71]
	s_setprio 0
	s_setprio 1
	v_mfma_f32_16x16x32_bf16 v[124:127], v[170:173], v[186:189], v[124:127]
	v_mfma_f32_16x16x32_bf16 v[116:119], v[178:181], v[186:189], v[116:119]
	v_mfma_f32_16x16x32_bf16 v[108:111], v[170:173], v[194:197], v[108:111]
	v_mfma_f32_16x16x32_bf16 v[96:99], v[178:181], v[194:197], v[96:99]
	v_mfma_f32_16x16x32_bf16 v[92:95], v[170:173], v[202:205], v[92:95]
	v_mfma_f32_16x16x32_bf16 v[80:83], v[178:181], v[202:205], v[80:83]
	v_mfma_f32_16x16x32_bf16 v[72:75], v[170:173], v[214:217], v[72:75]
	v_mfma_f32_16x16x32_bf16 v[64:67], v[178:181], v[214:217], v[64:67]
	v_mfma_f32_16x16x32_bf16 v[124:127], v[174:177], v[190:193], v[124:127]
	v_mfma_f32_16x16x32_bf16 v[116:119], v[182:185], v[190:193], v[116:119]
	v_mfma_f32_16x16x32_bf16 v[108:111], v[174:177], v[198:201], v[108:111]
	v_mfma_f32_16x16x32_bf16 v[96:99], v[182:185], v[198:201], v[96:99]
	v_mfma_f32_16x16x32_bf16 v[92:95], v[174:177], v[206:209], v[92:95]
	v_mfma_f32_16x16x32_bf16 v[80:83], v[182:185], v[206:209], v[80:83]
	v_mfma_f32_16x16x32_bf16 v[72:75], v[174:177], v[218:221], v[72:75]
	v_mfma_f32_16x16x32_bf16 v[64:67], v[182:185], v[218:221], v[64:67]
	s_setprio 0
	s_barrier
; #define PG8_STAGE(bufoff, gbase, voff) do { _Pragma("unroll") for (int _i = 0; _i < 2; ++_i) \
;         __builtin_amdgcn_global_load_lds((const unsigned*)((const char*)(gbase) + (voff)[_i]), (PG8_LAS unsigned*)(lds + (bufoff) + ldsw + _i * 8192), 16, 0, 0); } while (0)
; #define PG8_LDA(dst, b, h) do { _Pragma("unroll") for (int m = 0; m < 4; ++m) _Pragma("unroll") for (int k = 0; k < 2; ++k) dst[m][k] = *(const PG8_LAS bf16x8*)(lds + PG8_SA(b, h) + aoff + m * 2048 + k * 1024); } while (0)
; #define PG8_MMA(ai, bj, At, Bt) do { __builtin_amdgcn_s_setprio(1); _Pragma("unroll") for (int m = 0; m < 4; ++m) _Pragma("unroll") for (int n = 0; n < 2; ++n) _Pragma("unroll") for (int k = 0; k < 2; ++k) \
;         acc[ai][bj][m][n] = __builtin_amdgcn_mfma_f32_16x16x32_bf16(Bt[n][k], At[m][k], acc[ai][bj][m][n], 0, 0, 0); __builtin_amdgcn_s_setprio(0); } while (0)
; #define PG8_WAIT_V(n) asm volatile("s_waitcnt vmcnt(" #n ")" ::: "memory")
; #define PG8_WAIT_L(n) asm volatile("s_waitcnt lgkmcnt(" #n ")" ::: "memory")
; #define PG8_BAR __builtin_amdgcn_s_barrier()
; #define PG8_SCHED __builtin_amdgcn_sched_barrier(0)
; template <class Epi, class Sched, bool ALIGN_EPI = false, bool SP2 = false>
; __device__ __forceinline__ void gemm_phase(PG8_LAS unsigned char* lds, const Gemm g, const Sched& S, const Epi& E, int wave_s) {
;     ...
;             PG8_LDA(At, 1, 1); PG8_STAGE(PG8_SB(1, 0), b3, voffB); PG8_STAGE(PG8_SB(1, 1), b3 + hstep, voffB); PG8_STAGE(PG8_SA(1, 0), a3, voffA);
;             PG8_WAIT_V(8); PG8_WAIT_L(0); PG8_BAR; PG8_MMA(1, 0, At, B0); PG8_MMA(1, 1, At, B1); PG8_BAR; PG8_SCHED;
	s_add_i32 s40, s69, s45
	v_lshl_add_u64 v[144:145], v[144:145], 0, s[12:13]
	s_mov_b32 m0, s40
	ds_read_b128 v[186:189], v151 offset:49152
	ds_read_b128 v[190:193], v151 offset:50176
	ds_read_b128 v[194:197], v151 offset:51200
	ds_read_b128 v[198:201], v151 offset:52224
	ds_read_b128 v[202:205], v151 offset:53248
	ds_read_b128 v[206:209], v151 offset:54272
	ds_read_b128 v[214:217], v151 offset:55296
	ds_read_b128 v[218:221], v151 offset:56320
	global_load_lds_dwordx4 v[144:145], off
	s_add_i32 m0, s40, 0x2000
	s_add_u32 s38, s38, 0x40080
	v_lshl_add_u64 v[144:145], v[210:211], 0, s[12:13]
	s_addc_u32 s39, s39, 0
	s_add_i32 s40, s70, s45
	global_load_lds_dwordx4 v[144:145], off
	s_mov_b32 m0, s40
	v_lshl_add_u64 v[144:145], s[38:39], 0, v[132:133]
	global_load_lds_dwordx4 v[144:145], off
	s_add_i32 m0, s40, 0x2000
	v_lshl_add_u64 v[144:145], s[38:39], 0, v[128:129]
	global_load_lds_dwordx4 v[144:145], off
	s_mov_b32 m0, s56
	v_lshl_add_u64 v[144:145], v[222:223], 0, s[12:13]
	global_load_lds_dwordx4 v[144:145], off
	s_mov_b32 m0, s57
	v_lshl_add_u64 v[144:145], v[224:225], 0, s[12:13]
	global_load_lds_dwordx4 v[144:145], off
	s_waitcnt vmcnt(8)
	s_waitcnt lgkmcnt(0)
	s_barrier
	s_setprio 1
	s_waitcnt lgkmcnt(0)
	v_mfma_f32_16x16x32_bf16 v[60:63], v[154:157], v[186:189], v[60:63]
	v_mfma_f32_16x16x32_bf16 v[56:59], v[162:165], v[186:189], v[56:59]
	v_mfma_f32_16x16x32_bf16 v[44:47], v[154:157], v[194:197], v[44:47]
	v_mfma_f32_16x16x32_bf16 v[40:43], v[162:165], v[194:197], v[40:43]
	v_mfma_f32_16x16x32_bf16 v[28:31], v[154:157], v[202:205], v[28:31]
	v_mfma_f32_16x16x32_bf16 v[24:27], v[162:165], v[202:205], v[24:27]
	v_mfma_f32_16x16x32_bf16 v[12:15], v[154:157], v[214:217], v[12:15]
	v_mfma_f32_16x16x32_bf16 v[8:11], v[162:165], v[214:217], v[8:11]
	v_mfma_f32_16x16x32_bf16 v[60:63], v[158:161], v[190:193], v[60:63]
	v_mfma_f32_16x16x32_bf16 v[56:59], v[166:169], v[190:193], v[56:59]
	v_mfma_f32_16x16x32_bf16 v[44:47], v[158:161], v[198:201], v[44:47]
	v_mfma_f32_16x16x32_bf16 v[40:43], v[166:169], v[198:201], v[40:43]
	v_mfma_f32_16x16x32_bf16 v[28:31], v[158:161], v[206:209], v[28:31]
	v_mfma_f32_16x16x32_bf16 v[24:27], v[166:169], v[206:209], v[24:27]
	v_mfma_f32_16x16x32_bf16 v[12:15], v[158:161], v[218:221], v[12:15]
	v_mfma_f32_16x16x32_bf16 v[8:11], v[166:169], v[218:221], v[8:11]
	s_setprio 0
	s_setprio 1
	v_mfma_f32_16x16x32_bf16 v[52:55], v[170:173], v[186:189], v[52:55]
	v_mfma_f32_16x16x32_bf16 v[48:51], v[178:181], v[186:189], v[48:51]
	v_mfma_f32_16x16x32_bf16 v[36:39], v[170:173], v[194:197], v[36:39]
	v_mfma_f32_16x16x32_bf16 v[32:35], v[178:181], v[194:197], v[32:35]
	v_mfma_f32_16x16x32_bf16 v[20:23], v[170:173], v[202:205], v[20:23]
	v_mfma_f32_16x16x32_bf16 v[16:19], v[178:181], v[202:205], v[16:19]
	v_mfma_f32_16x16x32_bf16 v[4:7], v[170:173], v[214:217], v[4:7]
	v_mfma_f32_16x16x32_bf16 v[0:3], v[178:181], v[214:217], v[0:3]
	v_mfma_f32_16x16x32_bf16 v[52:55], v[174:177], v[190:193], v[52:55]
	v_mfma_f32_16x16x32_bf16 v[48:51], v[182:185], v[190:193], v[48:51]
	v_mfma_f32_16x16x32_bf16 v[36:39], v[174:177], v[198:201], v[36:39]
	v_mfma_f32_16x16x32_bf16 v[32:35], v[182:185], v[198:201], v[32:35]
	v_mfma_f32_16x16x32_bf16 v[20:23], v[174:177], v[206:209], v[20:23]
	v_mfma_f32_16x16x32_bf16 v[16:19], v[182:185], v[206:209], v[16:19]
	v_mfma_f32_16x16x32_bf16 v[4:7], v[174:177], v[218:221], v[4:7]
	v_mfma_f32_16x16x32_bf16 v[0:3], v[182:185], v[218:221], v[0:3]
	s_setprio 0
	s_barrier
	s_add_i32 s68, s68, 2
	s_add_u32 s36, s36, 0x100
	s_addc_u32 s37, s37, 0
	s_add_u32 s66, s66, 0x100
	s_addc_u32 s67, s67, 0
	s_cmp_gt_u32 s68, 13
	s_cbranch_scc0 .LBB0_1257
	s_and_b64 vcc, exec, s[16:17]
	s_cbranch_vccz .LBB0_1260
	s_barrier

; #define PG8_STAGE(bufoff, gbase, voff) do { _Pragma("unroll") for (int _i = 0; _i < 2; ++_i) \
;         __builtin_amdgcn_global_load_lds((const unsigned*)((const char*)(gbase) + (voff)[_i]), (PG8_LAS unsigned*)(lds + (bufoff) + ldsw + _i * 8192), 16, 0, 0); } while (0)
; #define PG8_LDA(dst, b, h) do { _Pragma("unroll") for (int m = 0; m < 4; ++m) _Pragma("unroll") for (int k = 0; k < 2; ++k) dst[m][k] = *(const PG8_LAS bf16x8*)(lds + PG8_SA(b, h) + aoff + m * 2048 + k * 1024); } while (0)
; #define PG8_LDB(dst, b, h) do { _Pragma("unroll") for (int n = 0; n < 2; ++n) _Pragma("unroll") for (int k = 0; k < 2; ++k) dst[n][k] = *(const PG8_LAS bf16x8*)(lds + PG8_SB(b, h) + boff + n * 2048 + k * 1024); } while (0)
; #define PG8_MMA(ai, bj, At, Bt) do { __builtin_amdgcn_s_setprio(1); _Pragma("unroll") for (int m = 0; m < 4; ++m) _Pragma("unroll") for (int n = 0; n < 2; ++n) _Pragma("unroll") for (int k = 0; k < 2; ++k) \
;         acc[ai][bj][m][n] = __builtin_amdgcn_mfma_f32_16x16x32_bf16(Bt[n][k], At[m][k], acc[ai][bj][m][n], 0, 0, 0); __builtin_amdgcn_s_setprio(0); } while (0)
; #define PG8_WAIT_V(n) asm volatile("s_waitcnt vmcnt(" #n ")" ::: "memory")
; #define PG8_WAIT_L(n) asm volatile("s_waitcnt lgkmcnt(" #n ")" ::: "memory")
; #define PG8_BAR __builtin_amdgcn_s_barrier()
; #define PG8_SCHED __builtin_amdgcn_sched_barrier(0)
; template <class Epi, class Sched, bool ALIGN_EPI = false, bool SP2 = false>
; __device__ __forceinline__ void gemm_phase(PG8_LAS unsigned char* lds, const Gemm g, const Sched& S, const Epi& E, int wave_s) {
;     ...
;             PG8_LDB(B0, 0, 0); PG8_LDB(B1, 0, 1); PG8_SCHED; PG8_LDA(At, 0, 0); PG8_STAGE(PG8_SA(1, 1), a1 + hstep, voffA);
;             PG8_WAIT_V(8); PG8_WAIT_L(0); PG8_BAR; PG8_MMA(0, 0, At, B0); PG8_MMA(0, 1, At, B1); PG8_BAR; PG8_SCHED;
;             PG8_LDA(At, 0, 1); PG8_STAGE(PG8_SB(0, 0), b2, voffB); PG8_STAGE(PG8_SB(0, 1), b2 + hstep, voffB); PG8_STAGE(PG8_SA(0, 0), a2, voffA);
.LBB0_1346:
	ds_read_b128 v[144:147], v151
	ds_read_b128 v[154:157], v151 offset:1024
	ds_read_b128 v[158:161], v151 offset:2048
	ds_read_b128 v[162:165], v151 offset:3072
	ds_read_b128 v[166:169], v152
	ds_read_b128 v[170:173], v152 offset:1024
	ds_read_b128 v[174:177], v152 offset:2048
	ds_read_b128 v[178:181], v152 offset:3072
	s_add_u32 s20, s18, 0x100
	s_addc_u32 s21, s19, 0
	s_cmp_eq_u32 s60, 40
	s_cselect_b32 s25, s5, s21
	s_cselect_b32 s24, s4, s20
	s_cselect_b32 s23, s17, s59
	s_cselect_b32 s22, s16, s58
	v_lshl_add_u64 v[210:211], s[18:19], 0, v[136:137]
	s_add_i32 m0, s37, 0xc000
	ds_read_b128 v[182:185], v153
	ds_read_b128 v[186:189], v153 offset:1024
	ds_read_b128 v[190:193], v153 offset:2048
	ds_read_b128 v[194:197], v153 offset:3072
	ds_read_b128 v[198:201], v153 offset:4096
	ds_read_b128 v[202:205], v153 offset:5120
	ds_read_b128 v[206:209], v153 offset:6144
	ds_read_b128 v[214:217], v153 offset:7168
	global_load_lds_dwordx4 v[210:211], off
	s_add_i32 m0, s37, 0xe000
	v_lshl_add_u64 v[210:211], s[18:19], 0, v[138:139]
	global_load_lds_dwordx4 v[210:211], off
	s_waitcnt vmcnt(8)
	s_waitcnt lgkmcnt(0)
	s_barrier
	s_setprio 1
	s_waitcnt lgkmcnt(0)
	v_mfma_f32_16x16x32_bf16 v[124:127], v[144:147], v[182:185], v[124:127]
	v_mfma_f32_16x16x32_bf16 v[120:123], v[158:161], v[182:185], v[120:123]
	v_mfma_f32_16x16x32_bf16 v[108:111], v[144:147], v[190:193], v[108:111]
	v_mfma_f32_16x16x32_bf16 v[104:107], v[158:161], v[190:193], v[104:107]
	v_mfma_f32_16x16x32_bf16 v[92:95], v[144:147], v[198:201], v[92:95]
	v_mfma_f32_16x16x32_bf16 v[88:91], v[158:161], v[198:201], v[88:91]
	v_mfma_f32_16x16x32_bf16 v[76:79], v[144:147], v[206:209], v[76:79]
	v_mfma_f32_16x16x32_bf16 v[72:75], v[158:161], v[206:209], v[72:75]
	v_mfma_f32_16x16x32_bf16 v[124:127], v[154:157], v[186:189], v[124:127]
	v_mfma_f32_16x16x32_bf16 v[120:123], v[162:165], v[186:189], v[120:123]
	v_mfma_f32_16x16x32_bf16 v[108:111], v[154:157], v[194:197], v[108:111]
	v_mfma_f32_16x16x32_bf16 v[104:107], v[162:165], v[194:197], v[104:107]
	v_mfma_f32_16x16x32_bf16 v[92:95], v[154:157], v[202:205], v[92:95]
	v_mfma_f32_16x16x32_bf16 v[88:91], v[162:165], v[202:205], v[88:91]
	v_mfma_f32_16x16x32_bf16 v[76:79], v[154:157], v[214:217], v[76:79]
	v_mfma_f32_16x16x32_bf16 v[72:75], v[162:165], v[214:217], v[72:75]
	s_setprio 0
	s_setprio 1
	v_mfma_f32_16x16x32_bf16 v[116:119], v[166:169], v[182:185], v[116:119]
	v_mfma_f32_16x16x32_bf16 v[112:115], v[174:177], v[182:185], v[112:115]
	v_mfma_f32_16x16x32_bf16 v[100:103], v[166:169], v[190:193], v[100:103]
	v_mfma_f32_16x16x32_bf16 v[96:99], v[174:177], v[190:193], v[96:99]
	v_mfma_f32_16x16x32_bf16 v[84:87], v[166:169], v[198:201], v[84:87]
	v_mfma_f32_16x16x32_bf16 v[80:83], v[174:177], v[198:201], v[80:83]
	v_mfma_f32_16x16x32_bf16 v[68:71], v[166:169], v[206:209], v[68:71]
	v_mfma_f32_16x16x32_bf16 v[64:67], v[174:177], v[206:209], v[64:67]
	v_mfma_f32_16x16x32_bf16 v[116:119], v[170:173], v[186:189], v[116:119]
	v_mfma_f32_16x16x32_bf16 v[112:115], v[178:181], v[186:189], v[112:115]
	v_mfma_f32_16x16x32_bf16 v[100:103], v[170:173], v[194:197], v[100:103]
	v_mfma_f32_16x16x32_bf16 v[96:99], v[178:181], v[194:197], v[96:99]
	v_mfma_f32_16x16x32_bf16 v[84:87], v[170:173], v[202:205], v[84:87]
	v_mfma_f32_16x16x32_bf16 v[80:83], v[178:181], v[202:205], v[80:83]
	v_mfma_f32_16x16x32_bf16 v[68:71], v[170:173], v[214:217], v[68:71]
	v_mfma_f32_16x16x32_bf16 v[64:67], v[178:181], v[214:217], v[64:67]
	s_setprio 0
	s_barrier
	s_add_i32 s18, s48, s36
	v_lshl_add_u64 v[210:211], s[22:23], 0, v[130:131]
	s_mov_b32 m0, s18
	ds_read_b128 v[182:185], v153 offset:16384
	ds_read_b128 v[186:189], v153 offset:17408
	ds_read_b128 v[190:193], v153 offset:18432
	ds_read_b128 v[194:197], v153 offset:19456
	ds_read_b128 v[198:201], v153 offset:20480
	ds_read_b128 v[202:205], v153 offset:21504
	ds_read_b128 v[206:209], v153 offset:22528
	ds_read_b128 v[214:217], v153 offset:23552
	global_load_lds_dwordx4 v[210:211], off
	s_add_i32 m0, s18, 0x2000
	s_add_u32 s18, s22, 0xb0000
	v_lshl_add_u64 v[218:219], s[22:23], 0, v[134:135]
	s_addc_u32 s19, s23, 0
	s_add_i32 s61, s49, s36
	global_load_lds_dwordx4 v[218:219], off
	v_lshl_add_u64 v[220:221], s[18:19], 0, v[130:131]
	s_mov_b32 m0, s61
	v_lshl_add_u64 v[222:223], s[24:25], 0, v[132:133]
	global_load_lds_dwordx4 v[220:221], off
	s_add_i32 m0, s61, 0x2000
	v_lshl_add_u64 v[220:221], s[18:19], 0, v[134:135]
	global_load_lds_dwordx4 v[220:221], off
	s_mov_b32 m0, s37
	v_lshl_add_u64 v[220:221], s[24:25], 0, v[128:129]
	global_load_lds_dwordx4 v[220:221], off
	s_mov_b32 m0, s38
	s_nop 0
	global_load_lds_dwordx4 v[222:223], off
	s_waitcnt vmcnt(8)
	s_waitcnt lgkmcnt(0)
	s_barrier
; #define PG8_STAGE(bufoff, gbase, voff) do { _Pragma("unroll") for (int _i = 0; _i < 2; ++_i) \
;         __builtin_amdgcn_global_load_lds((const unsigned*)((const char*)(gbase) + (voff)[_i]), (PG8_LAS unsigned*)(lds + (bufoff) + ldsw + _i * 8192), 16, 0, 0); } while (0)
; #define PG8_LDA(dst, b, h) do { _Pragma("unroll") for (int m = 0; m < 4; ++m) _Pragma("unroll") for (int k = 0; k < 2; ++k) dst[m][k] = *(const PG8_LAS bf16x8*)(lds + PG8_SA(b, h) + aoff + m * 2048 + k * 1024); } while (0)
; #define PG8_LDB(dst, b, h) do { _Pragma("unroll") for (int n = 0; n < 2; ++n) _Pragma("unroll") for (int k = 0; k < 2; ++k) dst[n][k] = *(const PG8_LAS bf16x8*)(lds + PG8_SB(b, h) + boff + n * 2048 + k * 1024); } while (0)
; #define PG8_MMA(ai, bj, At, Bt) do { __builtin_amdgcn_s_setprio(1); _Pragma("unroll") for (int m = 0; m < 4; ++m) _Pragma("unroll") for (int n = 0; n < 2; ++n) _Pragma("unroll") for (int k = 0; k < 2; ++k) \
;         acc[ai][bj][m][n] = __builtin_amdgcn_mfma_f32_16x16x32_bf16(Bt[n][k], At[m][k], acc[ai][bj][m][n], 0, 0, 0); __builtin_amdgcn_s_setprio(0); } while (0)
; #define PG8_WAIT_V(n) asm volatile("s_waitcnt vmcnt(" #n ")" ::: "memory")
; #define PG8_WAIT_L(n) asm volatile("s_waitcnt lgkmcnt(" #n ")" ::: "memory")
; #define PG8_BAR __builtin_amdgcn_s_barrier()
; #define PG8_SCHED __builtin_amdgcn_sched_barrier(0)
; template <class Epi, class Sched, bool ALIGN_EPI = false, bool SP2 = false>
; __device__ __forceinline__ void gemm_phase(PG8_LAS unsigned char* lds, const Gemm g, const Sched& S, const Epi& E, int wave_s) {
;     ...
;             PG8_WAIT_V(8); PG8_WAIT_L(0); PG8_BAR; PG8_MMA(1, 0, At, B0); PG8_MMA(1, 1, At, B1); PG8_BAR; PG8_SCHED;
;             PG8_LDB(B0, 1, 0); PG8_LDB(B1, 1, 1); PG8_SCHED; PG8_LDA(At, 1, 0); PG8_STAGE(PG8_SA(0, 1), a2 + hstep, voffA);
;             PG8_WAIT_V(8); PG8_WAIT_L(0); PG8_BAR; PG8_MMA(0, 0, At, B0); PG8_MMA(0, 1, At, B1); PG8_BAR; PG8_SCHED;
	s_setprio 1
	s_waitcnt lgkmcnt(0)
	v_mfma_f32_16x16x32_bf16 v[60:63], v[144:147], v[182:185], v[60:63]
	v_mfma_f32_16x16x32_bf16 v[56:59], v[158:161], v[182:185], v[56:59]
	v_mfma_f32_16x16x32_bf16 v[44:47], v[144:147], v[190:193], v[44:47]
	v_mfma_f32_16x16x32_bf16 v[40:43], v[158:161], v[190:193], v[40:43]
	v_mfma_f32_16x16x32_bf16 v[28:31], v[144:147], v[198:201], v[28:31]
	v_mfma_f32_16x16x32_bf16 v[24:27], v[158:161], v[198:201], v[24:27]
	v_mfma_f32_16x16x32_bf16 v[12:15], v[144:147], v[206:209], v[12:15]
	v_mfma_f32_16x16x32_bf16 v[8:11], v[158:161], v[206:209], v[8:11]
	v_mfma_f32_16x16x32_bf16 v[60:63], v[154:157], v[186:189], v[60:63]
	v_mfma_f32_16x16x32_bf16 v[56:59], v[162:165], v[186:189], v[56:59]
	v_mfma_f32_16x16x32_bf16 v[44:47], v[154:157], v[194:197], v[44:47]
	v_mfma_f32_16x16x32_bf16 v[40:43], v[162:165], v[194:197], v[40:43]
	v_mfma_f32_16x16x32_bf16 v[28:31], v[154:157], v[202:205], v[28:31]
	v_mfma_f32_16x16x32_bf16 v[24:27], v[162:165], v[202:205], v[24:27]
	v_mfma_f32_16x16x32_bf16 v[12:15], v[154:157], v[214:217], v[12:15]
	v_mfma_f32_16x16x32_bf16 v[8:11], v[162:165], v[214:217], v[8:11]
	s_setprio 0
	s_setprio 1
	v_mfma_f32_16x16x32_bf16 v[52:55], v[166:169], v[182:185], v[52:55]
	v_mfma_f32_16x16x32_bf16 v[48:51], v[174:177], v[182:185], v[48:51]
	v_mfma_f32_16x16x32_bf16 v[36:39], v[166:169], v[190:193], v[36:39]
	v_mfma_f32_16x16x32_bf16 v[32:35], v[174:177], v[190:193], v[32:35]
	v_mfma_f32_16x16x32_bf16 v[20:23], v[166:169], v[198:201], v[20:23]
	v_mfma_f32_16x16x32_bf16 v[16:19], v[174:177], v[198:201], v[16:19]
	v_mfma_f32_16x16x32_bf16 v[4:7], v[166:169], v[206:209], v[4:7]
	v_mfma_f32_16x16x32_bf16 v[0:3], v[174:177], v[206:209], v[0:3]
	v_mfma_f32_16x16x32_bf16 v[52:55], v[170:173], v[186:189], v[52:55]
	v_mfma_f32_16x16x32_bf16 v[48:51], v[178:181], v[186:189], v[48:51]
	v_mfma_f32_16x16x32_bf16 v[36:39], v[170:173], v[194:197], v[36:39]
	v_mfma_f32_16x16x32_bf16 v[32:35], v[178:181], v[194:197], v[32:35]
	v_mfma_f32_16x16x32_bf16 v[20:23], v[170:173], v[202:205], v[20:23]
	v_mfma_f32_16x16x32_bf16 v[16:19], v[178:181], v[202:205], v[16:19]
	v_mfma_f32_16x16x32_bf16 v[4:7], v[170:173], v[214:217], v[4:7]
	v_mfma_f32_16x16x32_bf16 v[0:3], v[178:181], v[214:217], v[0:3]
	s_setprio 0
	s_barrier
	s_add_i32 s61, 0, 0x18000
	s_add_i32 s62, 0, 0x1c000
	v_add_u32_e32 v162, s61, v149
	v_add_u32_e32 v178, s62, v149
	ds_read_b128 v[144:147], v162
	ds_read_b128 v[154:157], v162 offset:1024
	ds_read_b128 v[158:161], v162 offset:2048
	ds_read_b128 v[162:165], v162 offset:3072
	ds_read_b128 v[166:169], v178
	ds_read_b128 v[170:173], v178 offset:1024
	ds_read_b128 v[174:177], v178 offset:2048
	ds_read_b128 v[178:181], v178 offset:3072
	s_add_u32 s18, s24, 0xb0000
	s_addc_u32 s19, s25, 0
	s_mov_b32 m0, s39
	v_lshl_add_u64 v[224:225], s[18:19], 0, v[128:129]
	ds_read_b128 v[182:185], v153 offset:32768
	ds_read_b128 v[186:189], v153 offset:33792
	ds_read_b128 v[190:193], v153 offset:34816
	ds_read_b128 v[194:197], v153 offset:35840
	ds_read_b128 v[198:201], v153 offset:36864
	ds_read_b128 v[202:205], v153 offset:37888
	ds_read_b128 v[206:209], v153 offset:38912
	ds_read_b128 v[214:217], v153 offset:39936
	global_load_lds_dwordx4 v[224:225], off
	s_mov_b32 m0, s40
	v_lshl_add_u64 v[224:225], s[18:19], 0, v[132:133]
	global_load_lds_dwordx4 v[224:225], off
	s_waitcnt vmcnt(8)
	s_waitcnt lgkmcnt(0)
	s_barrier
	s_setprio 1
	s_waitcnt lgkmcnt(0)
	v_mfma_f32_16x16x32_bf16 v[124:127], v[144:147], v[182:185], v[124:127]
	v_mfma_f32_16x16x32_bf16 v[120:123], v[158:161], v[182:185], v[120:123]
	v_mfma_f32_16x16x32_bf16 v[108:111], v[144:147], v[190:193], v[108:111]
	v_mfma_f32_16x16x32_bf16 v[104:107], v[158:161], v[190:193], v[104:107]
	v_mfma_f32_16x16x32_bf16 v[92:95], v[144:147], v[198:201], v[92:95]
	v_mfma_f32_16x16x32_bf16 v[88:91], v[158:161], v[198:201], v[88:91]
	v_mfma_f32_16x16x32_bf16 v[76:79], v[144:147], v[206:209], v[76:79]
	v_mfma_f32_16x16x32_bf16 v[72:75], v[158:161], v[206:209], v[72:75]
	v_mfma_f32_16x16x32_bf16 v[124:127], v[154:157], v[186:189], v[124:127]
	v_mfma_f32_16x16x32_bf16 v[120:123], v[162:165], v[186:189], v[120:123]
	v_mfma_f32_16x16x32_bf16 v[108:111], v[154:157], v[194:197], v[108:111]
	v_mfma_f32_16x16x32_bf16 v[104:107], v[162:165], v[194:197], v[104:107]
	v_mfma_f32_16x16x32_bf16 v[92:95], v[154:157], v[202:205], v[92:95]
	v_mfma_f32_16x16x32_bf16 v[88:91], v[162:165], v[202:205], v[88:91]
	v_mfma_f32_16x16x32_bf16 v[76:79], v[154:157], v[214:217], v[76:79]
	v_mfma_f32_16x16x32_bf16 v[72:75], v[162:165], v[214:217], v[72:75]
	s_setprio 0
	s_setprio 1
	v_mfma_f32_16x16x32_bf16 v[116:119], v[166:169], v[182:185], v[116:119]
	v_mfma_f32_16x16x32_bf16 v[112:115], v[174:177], v[182:185], v[112:115]
	v_mfma_f32_16x16x32_bf16 v[100:103], v[166:169], v[190:193], v[100:103]
	v_mfma_f32_16x16x32_bf16 v[96:99], v[174:177], v[190:193], v[96:99]
	v_mfma_f32_16x16x32_bf16 v[84:87], v[166:169], v[198:201], v[84:87]
	v_mfma_f32_16x16x32_bf16 v[80:83], v[174:177], v[198:201], v[80:83]
	v_mfma_f32_16x16x32_bf16 v[68:71], v[166:169], v[206:209], v[68:71]
	v_mfma_f32_16x16x32_bf16 v[64:67], v[174:177], v[206:209], v[64:67]
	v_mfma_f32_16x16x32_bf16 v[116:119], v[170:173], v[186:189], v[116:119]
	v_mfma_f32_16x16x32_bf16 v[112:115], v[178:181], v[186:189], v[112:115]
	v_mfma_f32_16x16x32_bf16 v[100:103], v[170:173], v[194:197], v[100:103]
	v_mfma_f32_16x16x32_bf16 v[96:99], v[178:181], v[194:197], v[96:99]
	v_mfma_f32_16x16x32_bf16 v[84:87], v[170:173], v[202:205], v[84:87]
	v_mfma_f32_16x16x32_bf16 v[80:83], v[178:181], v[202:205], v[80:83]
	v_mfma_f32_16x16x32_bf16 v[68:71], v[170:173], v[214:217], v[68:71]
	v_mfma_f32_16x16x32_bf16 v[64:67], v[178:181], v[214:217], v[64:67]
	s_setprio 0
	s_barrier
; #define PG8_STAGE(bufoff, gbase, voff) do { _Pragma("unroll") for (int _i = 0; _i < 2; ++_i) \
;         __builtin_amdgcn_global_load_lds((const unsigned*)((const char*)(gbase) + (voff)[_i]), (PG8_LAS unsigned*)(lds + (bufoff) + ldsw + _i * 8192), 16, 0, 0); } while (0)
; #define PG8_LDA(dst, b, h) do { _Pragma("unroll") for (int m = 0; m < 4; ++m) _Pragma("unroll") for (int k = 0; k < 2; ++k) dst[m][k] = *(const PG8_LAS bf16x8*)(lds + PG8_SA(b, h) + aoff + m * 2048 + k * 1024); } while (0)
; #define PG8_MMA(ai, bj, At, Bt) do { __builtin_amdgcn_s_setprio(1); _Pragma("unroll") for (int m = 0; m < 4; ++m) _Pragma("unroll") for (int n = 0; n < 2; ++n) _Pragma("unroll") for (int k = 0; k < 2; ++k) \
;         acc[ai][bj][m][n] = __builtin_amdgcn_mfma_f32_16x16x32_bf16(Bt[n][k], At[m][k], acc[ai][bj][m][n], 0, 0, 0); __builtin_amdgcn_s_setprio(0); } while (0)
; #define PG8_WAIT_V(n) asm volatile("s_waitcnt vmcnt(" #n ")" ::: "memory")
; #define PG8_WAIT_L(n) asm volatile("s_waitcnt lgkmcnt(" #n ")" ::: "memory")
; #define PG8_BAR __builtin_amdgcn_s_barrier()
; #define PG8_SCHED __builtin_amdgcn_sched_barrier(0)
; template <class Epi, class Sched, bool ALIGN_EPI = false, bool SP2 = false>
; __device__ __forceinline__ void gemm_phase(PG8_LAS unsigned char* lds, const Gemm g, const Sched& S, const Epi& E, int wave_s) {
;     ...
;             PG8_LDA(At, 1, 1); PG8_STAGE(PG8_SB(1, 0), b3, voffB); PG8_STAGE(PG8_SB(1, 1), b3 + hstep, voffB); PG8_STAGE(PG8_SA(1, 0), a3, voffA);
;             PG8_WAIT_V(8); PG8_WAIT_L(0); PG8_BAR; PG8_MMA(1, 0, At, B0); PG8_MMA(1, 1, At, B1); PG8_BAR; PG8_SCHED;
	s_add_i32 s18, s61, s36
	v_lshl_add_u64 v[210:211], v[210:211], 0, s[10:11]
	s_mov_b32 m0, s18
	ds_read_b128 v[182:185], v153 offset:49152
	ds_read_b128 v[186:189], v153 offset:50176
	ds_read_b128 v[190:193], v153 offset:51200
	ds_read_b128 v[194:197], v153 offset:52224
	ds_read_b128 v[198:201], v153 offset:53248
	ds_read_b128 v[202:205], v153 offset:54272
	ds_read_b128 v[206:209], v153 offset:55296
	ds_read_b128 v[214:217], v153 offset:56320
	global_load_lds_dwordx4 v[210:211], off
	s_add_i32 m0, s18, 0x2000
	s_add_u32 s18, s22, 0xb0080
	v_lshl_add_u64 v[210:211], v[218:219], 0, s[10:11]
	s_addc_u32 s19, s23, 0
	s_add_i32 s22, s62, s36
	global_load_lds_dwordx4 v[210:211], off
	s_mov_b32 m0, s22
	v_lshl_add_u64 v[210:211], s[18:19], 0, v[130:131]
	global_load_lds_dwordx4 v[210:211], off
	s_add_i32 m0, s22, 0x2000
	v_lshl_add_u64 v[210:211], s[18:19], 0, v[134:135]
	global_load_lds_dwordx4 v[210:211], off
	s_mov_b32 m0, s42
	v_lshl_add_u64 v[210:211], v[220:221], 0, s[10:11]
	global_load_lds_dwordx4 v[210:211], off
	s_mov_b32 m0, s43
	v_lshl_add_u64 v[210:211], v[222:223], 0, s[10:11]
	global_load_lds_dwordx4 v[210:211], off
	s_waitcnt vmcnt(8)
	s_waitcnt lgkmcnt(0)
	s_barrier
	s_setprio 1
	s_waitcnt lgkmcnt(0)
	v_mfma_f32_16x16x32_bf16 v[60:63], v[144:147], v[182:185], v[60:63]
	v_mfma_f32_16x16x32_bf16 v[56:59], v[158:161], v[182:185], v[56:59]
	v_mfma_f32_16x16x32_bf16 v[44:47], v[144:147], v[190:193], v[44:47]
	v_mfma_f32_16x16x32_bf16 v[40:43], v[158:161], v[190:193], v[40:43]
	v_mfma_f32_16x16x32_bf16 v[28:31], v[144:147], v[198:201], v[28:31]
	v_mfma_f32_16x16x32_bf16 v[24:27], v[158:161], v[198:201], v[24:27]
	v_mfma_f32_16x16x32_bf16 v[12:15], v[144:147], v[206:209], v[12:15]
	v_mfma_f32_16x16x32_bf16 v[8:11], v[158:161], v[206:209], v[8:11]
	v_mfma_f32_16x16x32_bf16 v[60:63], v[154:157], v[186:189], v[60:63]
	v_mfma_f32_16x16x32_bf16 v[56:59], v[162:165], v[186:189], v[56:59]
	v_mfma_f32_16x16x32_bf16 v[44:47], v[154:157], v[194:197], v[44:47]
	v_mfma_f32_16x16x32_bf16 v[40:43], v[162:165], v[194:197], v[40:43]
	v_mfma_f32_16x16x32_bf16 v[28:31], v[154:157], v[202:205], v[28:31]
	v_mfma_f32_16x16x32_bf16 v[24:27], v[162:165], v[202:205], v[24:27]
	v_mfma_f32_16x16x32_bf16 v[12:15], v[154:157], v[214:217], v[12:15]
	v_mfma_f32_16x16x32_bf16 v[8:11], v[162:165], v[214:217], v[8:11]
	s_setprio 0
	s_setprio 1
	v_mfma_f32_16x16x32_bf16 v[52:55], v[166:169], v[182:185], v[52:55]
	v_mfma_f32_16x16x32_bf16 v[48:51], v[174:177], v[182:185], v[48:51]
	v_mfma_f32_16x16x32_bf16 v[36:39], v[166:169], v[190:193], v[36:39]
	v_mfma_f32_16x16x32_bf16 v[32:35], v[174:177], v[190:193], v[32:35]
	v_mfma_f32_16x16x32_bf16 v[20:23], v[166:169], v[198:201], v[20:23]
	v_mfma_f32_16x16x32_bf16 v[16:19], v[174:177], v[198:201], v[16:19]
	v_mfma_f32_16x16x32_bf16 v[4:7], v[166:169], v[206:209], v[4:7]
	v_mfma_f32_16x16x32_bf16 v[0:3], v[174:177], v[206:209], v[0:3]
	v_mfma_f32_16x16x32_bf16 v[52:55], v[170:173], v[186:189], v[52:55]
	v_mfma_f32_16x16x32_bf16 v[48:51], v[178:181], v[186:189], v[48:51]
	v_mfma_f32_16x16x32_bf16 v[36:39], v[170:173], v[194:197], v[36:39]
	v_mfma_f32_16x16x32_bf16 v[32:35], v[178:181], v[194:197], v[32:35]
	v_mfma_f32_16x16x32_bf16 v[20:23], v[170:173], v[202:205], v[20:23]
	v_mfma_f32_16x16x32_bf16 v[16:19], v[178:181], v[202:205], v[16:19]
	v_mfma_f32_16x16x32_bf16 v[4:7], v[170:173], v[214:217], v[4:7]
	v_mfma_f32_16x16x32_bf16 v[0:3], v[178:181], v[214:217], v[0:3]
	s_setprio 0
	s_barrier
	s_add_i32 s60, s60, 2
	s_add_u32 s58, s58, 0x100
	s_addc_u32 s59, s59, 0
	s_cmp_gt_u32 s60, 41
	s_mov_b64 s[18:19], s[20:21]
	s_cbranch_scc0 .LBB0_1346
	s_and_b64 vcc, exec, s[12:13]
	s_cbranch_vccz .LBB0_1349
	s_barrier
